# GEMM loops: priority raised during the load/LDS-read phase instead of the MFMA phase
# speedup vs baseline: 1.0011x; 1.0011x over previous
; #define PG8_STAGE(bufoff, gbase, voff) do { _Pragma("unroll") for (int _i = 0; _i < 2; ++_i) \
;         __builtin_amdgcn_global_load_lds((const unsigned*)((const char*)(gbase) + (voff)[_i]), (LAS unsigned*)(lds + (bufoff) + ldsw + _i * 8192), 16, 0, 0); } while (0)
; #define PG8_LDA(dst, b, h) do { _Pragma("unroll") for (int m = 0; m < 4; ++m) _Pragma("unroll") for (int k = 0; k < 2; ++k) dst[m][k] = *(const LAS bf16x8*)(lds + PG8_SA(b, h) + aoff + m * 2048 + k * 1024); } while (0)
; #define PG8_LDB(dst, b, h) do { _Pragma("unroll") for (int n = 0; n < 2; ++n) _Pragma("unroll") for (int k = 0; k < 2; ++k) dst[n][k] = *(const LAS bf16x8*)(lds + PG8_SB(b, h) + boff + n * 2048 + k * 1024); } while (0)
; #define PG8_MMA(ai, bj, At, Bt) do { __builtin_amdgcn_s_setprio(1); _Pragma("unroll") for (int m = 0; m < 4; ++m) _Pragma("unroll") for (int n = 0; n < 2; ++n) _Pragma("unroll") for (int k = 0; k < 2; ++k) \
;         acc[ai][bj][m][n] = __builtin_amdgcn_mfma_f32_16x16x32_bf16(Bt[n][k], At[m][k], acc[ai][bj][m][n], 0, 0, 0); __builtin_amdgcn_s_setprio(0); } while (0)
; #define PG8_WAIT_V(n) asm volatile("s_waitcnt vmcnt(" #n ")" ::: "memory")
; #define PG8_WAIT_L(n) asm volatile("s_waitcnt lgkmcnt(" #n ")" ::: "memory")
; #define PG8_BAR __builtin_amdgcn_s_barrier()
; #define PG8_SCHED __builtin_amdgcn_sched_barrier(0)
; __device__ __forceinline__ void gemm_phase(LAS unsigned char* lds, const Params& p, const bf16_t* gA, const bf16_t* gBt, const int gM, const int gN, const int gK, const int epi, const int perm, bf16_t* const Hp, const int goff, const float coef) {
;     ...
;             const bool last = (t == nt - 2);
;             const char* a1 = cA + (size_t)(t + 1) * kstep;
;             const char* a2 = last ? nA : cA + (size_t)(t + 2) * kstep; const char* b2 = last ? nB : cB + (size_t)(t + 2) * kstep;
;             const char* a3 = a2 + kstep; const char* b3 = b2 + kstep;
;             PG8_LDB(B0, 0, 0); PG8_LDB(B1, 0, 1); PG8_SCHED; PG8_LDA(At, 0, 0); PG8_STAGE(PG8_SA(1, 1), a1 + hstep, voffA);
;             PG8_WAIT_V(8); PG8_WAIT_L(0); PG8_BAR; PG8_MMA(0, 0, At, B0); PG8_MMA(0, 1, At, B1); PG8_BAR; PG8_SCHED;
;             PG8_LDA(At, 0, 1); PG8_STAGE(PG8_SB(0, 0), b2, voffB); PG8_STAGE(PG8_SB(0, 1), b2 + hstep, voffB); PG8_STAGE(PG8_SA(0, 0), a2, voffA);
.LBB0_170:
	ds_read_b128 v[158:161], v155
	ds_read_b128 v[162:165], v155 offset:1024
	ds_read_b128 v[166:169], v155 offset:2048
	ds_read_b128 v[170:173], v155 offset:3072
	ds_read_b128 v[174:177], v156
	ds_read_b128 v[178:181], v156 offset:1024
	ds_read_b128 v[182:185], v156 offset:2048
	ds_read_b128 v[186:189], v156 offset:3072
	s_add_i32 s56, s48, 2
	s_add_u32 s46, s44, 0xfff80080
	s_addc_u32 s47, s45, -1
	s_cmp_eq_u32 s53, s48
	s_cselect_b32 s48, s50, s46
	s_cselect_b32 s49, s25, s47
	s_cselect_b32 s47, s27, s55
	s_cselect_b32 s46, s51, s54
	v_lshl_add_u64 v[144:145], s[44:45], 0, v[136:137]
	s_add_i32 m0, s14, 0xc000
	ds_read_b128 v[190:193], v157
	ds_read_b128 v[194:197], v157 offset:1024
	ds_read_b128 v[198:201], v157 offset:2048
	ds_read_b128 v[202:205], v157 offset:3072
	ds_read_b128 v[206:209], v157 offset:4096
	ds_read_b128 v[210:213], v157 offset:5120
	ds_read_b128 v[214:217], v157 offset:6144
	ds_read_b128 v[218:221], v157 offset:7168
	global_load_lds_dwordx4 v[144:145], off
	v_lshl_add_u64 v[144:145], s[44:45], 0, v[138:139]
	s_add_i32 m0, s14, 0xe000
	s_nop 0
	global_load_lds_dwordx4 v[144:145], off
	s_waitcnt vmcnt(8)
	s_waitcnt lgkmcnt(0)
	s_barrier
	s_setprio 0
	s_waitcnt lgkmcnt(0)
	v_mfma_f32_16x16x32_bf16 v[124:127], v[158:161], v[190:193], v[124:127]
	v_mfma_f32_16x16x32_bf16 v[120:123], v[166:169], v[190:193], v[120:123]
	v_mfma_f32_16x16x32_bf16 v[108:111], v[158:161], v[198:201], v[108:111]
	v_mfma_f32_16x16x32_bf16 v[104:107], v[166:169], v[198:201], v[104:107]
	v_mfma_f32_16x16x32_bf16 v[92:95], v[158:161], v[206:209], v[92:95]
	v_mfma_f32_16x16x32_bf16 v[88:91], v[166:169], v[206:209], v[88:91]
	v_mfma_f32_16x16x32_bf16 v[76:79], v[158:161], v[214:217], v[76:79]
	v_mfma_f32_16x16x32_bf16 v[72:75], v[166:169], v[214:217], v[72:75]
	v_mfma_f32_16x16x32_bf16 v[124:127], v[162:165], v[194:197], v[124:127]
	v_mfma_f32_16x16x32_bf16 v[120:123], v[170:173], v[194:197], v[120:123]
	v_mfma_f32_16x16x32_bf16 v[108:111], v[162:165], v[202:205], v[108:111]
	v_mfma_f32_16x16x32_bf16 v[104:107], v[170:173], v[202:205], v[104:107]
	v_mfma_f32_16x16x32_bf16 v[92:95], v[162:165], v[210:213], v[92:95]
	v_mfma_f32_16x16x32_bf16 v[88:91], v[170:173], v[210:213], v[88:91]
	v_mfma_f32_16x16x32_bf16 v[76:79], v[162:165], v[218:221], v[76:79]
	v_mfma_f32_16x16x32_bf16 v[72:75], v[170:173], v[218:221], v[72:75]
	v_mfma_f32_16x16x32_bf16 v[116:119], v[174:177], v[190:193], v[116:119]
	v_mfma_f32_16x16x32_bf16 v[112:115], v[182:185], v[190:193], v[112:115]
	v_mfma_f32_16x16x32_bf16 v[100:103], v[174:177], v[198:201], v[100:103]
	v_mfma_f32_16x16x32_bf16 v[96:99], v[182:185], v[198:201], v[96:99]
	v_mfma_f32_16x16x32_bf16 v[84:87], v[174:177], v[206:209], v[84:87]
	v_mfma_f32_16x16x32_bf16 v[80:83], v[182:185], v[206:209], v[80:83]
	v_mfma_f32_16x16x32_bf16 v[68:71], v[174:177], v[214:217], v[68:71]
	v_mfma_f32_16x16x32_bf16 v[64:67], v[182:185], v[214:217], v[64:67]
	v_mfma_f32_16x16x32_bf16 v[116:119], v[178:181], v[194:197], v[116:119]
	v_mfma_f32_16x16x32_bf16 v[112:115], v[186:189], v[194:197], v[112:115]
	v_mfma_f32_16x16x32_bf16 v[100:103], v[178:181], v[202:205], v[100:103]
	v_mfma_f32_16x16x32_bf16 v[96:99], v[186:189], v[202:205], v[96:99]
	v_mfma_f32_16x16x32_bf16 v[84:87], v[178:181], v[210:213], v[84:87]
	v_mfma_f32_16x16x32_bf16 v[80:83], v[186:189], v[210:213], v[80:83]
	v_mfma_f32_16x16x32_bf16 v[68:71], v[178:181], v[218:221], v[68:71]
	v_mfma_f32_16x16x32_bf16 v[64:67], v[186:189], v[218:221], v[64:67]
	s_setprio 1
	s_barrier
	s_add_i32 s57, s23, s11
	v_lshl_add_u64 v[144:145], s[46:47], 0, v[130:131]
	s_mov_b32 m0, s57
	ds_read_b128 v[190:193], v157 offset:16384
	ds_read_b128 v[194:197], v157 offset:17408
	ds_read_b128 v[198:201], v157 offset:18432
	ds_read_b128 v[202:205], v157 offset:19456
	ds_read_b128 v[206:209], v157 offset:20480
	ds_read_b128 v[210:213], v157 offset:21504
	ds_read_b128 v[214:217], v157 offset:22528
	ds_read_b128 v[218:221], v157 offset:23552
	global_load_lds_dwordx4 v[144:145], off
	s_add_i32 m0, s57, 0x2000
	s_add_u32 s58, s46, 0x80000
	v_lshl_add_u64 v[222:223], s[46:47], 0, v[134:135]
	s_addc_u32 s59, s47, 0
	s_add_i32 s57, s33, s11
	global_load_lds_dwordx4 v[222:223], off
	v_lshl_add_u64 v[224:225], s[58:59], 0, v[130:131]
	s_mov_b32 m0, s57
	v_lshl_add_u64 v[226:227], s[48:49], 0, v[132:133]
	global_load_lds_dwordx4 v[224:225], off
	v_lshl_add_u64 v[224:225], s[58:59], 0, v[134:135]
	s_add_i32 m0, s57, 0x2000
	s_nop 0
	global_load_lds_dwordx4 v[224:225], off
	v_lshl_add_u64 v[224:225], s[48:49], 0, v[128:129]
	s_mov_b32 m0, s14
	s_nop 0
	global_load_lds_dwordx4 v[224:225], off
	s_mov_b32 m0, s15
	s_nop 0
	global_load_lds_dwordx4 v[226:227], off
	s_waitcnt vmcnt(8)
	s_waitcnt lgkmcnt(0)
	s_barrier
; #define PG8_STAGE(bufoff, gbase, voff) do { _Pragma("unroll") for (int _i = 0; _i < 2; ++_i) \
;         __builtin_amdgcn_global_load_lds((const unsigned*)((const char*)(gbase) + (voff)[_i]), (LAS unsigned*)(lds + (bufoff) + ldsw + _i * 8192), 16, 0, 0); } while (0)
; #define PG8_LDA(dst, b, h) do { _Pragma("unroll") for (int m = 0; m < 4; ++m) _Pragma("unroll") for (int k = 0; k < 2; ++k) dst[m][k] = *(const LAS bf16x8*)(lds + PG8_SA(b, h) + aoff + m * 2048 + k * 1024); } while (0)
; #define PG8_LDB(dst, b, h) do { _Pragma("unroll") for (int n = 0; n < 2; ++n) _Pragma("unroll") for (int k = 0; k < 2; ++k) dst[n][k] = *(const LAS bf16x8*)(lds + PG8_SB(b, h) + boff + n * 2048 + k * 1024); } while (0)
; #define PG8_MMA(ai, bj, At, Bt) do { __builtin_amdgcn_s_setprio(1); _Pragma("unroll") for (int m = 0; m < 4; ++m) _Pragma("unroll") for (int n = 0; n < 2; ++n) _Pragma("unroll") for (int k = 0; k < 2; ++k) \
;         acc[ai][bj][m][n] = __builtin_amdgcn_mfma_f32_16x16x32_bf16(Bt[n][k], At[m][k], acc[ai][bj][m][n], 0, 0, 0); __builtin_amdgcn_s_setprio(0); } while (0)
; #define PG8_WAIT_V(n) asm volatile("s_waitcnt vmcnt(" #n ")" ::: "memory")
; #define PG8_WAIT_L(n) asm volatile("s_waitcnt lgkmcnt(" #n ")" ::: "memory")
; #define PG8_BAR __builtin_amdgcn_s_barrier()
; #define PG8_SCHED __builtin_amdgcn_sched_barrier(0)
; __device__ __forceinline__ void gemm_phase(LAS unsigned char* lds, const Params& p, const bf16_t* gA, const bf16_t* gBt, const int gM, const int gN, const int gK, const int epi, const int perm, bf16_t* const Hp, const int goff, const float coef) {
;     ...
;             PG8_WAIT_V(8); PG8_WAIT_L(0); PG8_BAR; PG8_MMA(1, 0, At, B0); PG8_MMA(1, 1, At, B1); PG8_BAR; PG8_SCHED;
;             PG8_LDB(B0, 1, 0); PG8_LDB(B1, 1, 1); PG8_SCHED; PG8_LDA(At, 1, 0); PG8_STAGE(PG8_SA(0, 1), a2 + hstep, voffA);
;             PG8_WAIT_V(8); PG8_WAIT_L(0); PG8_BAR; PG8_MMA(0, 0, At, B0); PG8_MMA(0, 1, At, B1); PG8_BAR; PG8_SCHED;
	s_setprio 0
	s_waitcnt lgkmcnt(0)
	v_mfma_f32_16x16x32_bf16 v[60:63], v[158:161], v[190:193], v[60:63]
	v_mfma_f32_16x16x32_bf16 v[56:59], v[166:169], v[190:193], v[56:59]
	v_mfma_f32_16x16x32_bf16 v[44:47], v[158:161], v[198:201], v[44:47]
	v_mfma_f32_16x16x32_bf16 v[40:43], v[166:169], v[198:201], v[40:43]
	v_mfma_f32_16x16x32_bf16 v[28:31], v[158:161], v[206:209], v[28:31]
	v_mfma_f32_16x16x32_bf16 v[24:27], v[166:169], v[206:209], v[24:27]
	v_mfma_f32_16x16x32_bf16 v[12:15], v[158:161], v[214:217], v[12:15]
	v_mfma_f32_16x16x32_bf16 v[8:11], v[166:169], v[214:217], v[8:11]
	v_mfma_f32_16x16x32_bf16 v[60:63], v[162:165], v[194:197], v[60:63]
	v_mfma_f32_16x16x32_bf16 v[56:59], v[170:173], v[194:197], v[56:59]
	v_mfma_f32_16x16x32_bf16 v[44:47], v[162:165], v[202:205], v[44:47]
	v_mfma_f32_16x16x32_bf16 v[40:43], v[170:173], v[202:205], v[40:43]
	v_mfma_f32_16x16x32_bf16 v[28:31], v[162:165], v[210:213], v[28:31]
	v_mfma_f32_16x16x32_bf16 v[24:27], v[170:173], v[210:213], v[24:27]
	v_mfma_f32_16x16x32_bf16 v[12:15], v[162:165], v[218:221], v[12:15]
	v_mfma_f32_16x16x32_bf16 v[8:11], v[170:173], v[218:221], v[8:11]
	v_mfma_f32_16x16x32_bf16 v[52:55], v[174:177], v[190:193], v[52:55]
	v_mfma_f32_16x16x32_bf16 v[48:51], v[182:185], v[190:193], v[48:51]
	v_mfma_f32_16x16x32_bf16 v[36:39], v[174:177], v[198:201], v[36:39]
	v_mfma_f32_16x16x32_bf16 v[32:35], v[182:185], v[198:201], v[32:35]
	v_mfma_f32_16x16x32_bf16 v[20:23], v[174:177], v[206:209], v[20:23]
	v_mfma_f32_16x16x32_bf16 v[16:19], v[182:185], v[206:209], v[16:19]
	v_mfma_f32_16x16x32_bf16 v[4:7], v[174:177], v[214:217], v[4:7]
	v_mfma_f32_16x16x32_bf16 v[0:3], v[182:185], v[214:217], v[0:3]
	v_mfma_f32_16x16x32_bf16 v[52:55], v[178:181], v[194:197], v[52:55]
	v_mfma_f32_16x16x32_bf16 v[48:51], v[186:189], v[194:197], v[48:51]
	v_mfma_f32_16x16x32_bf16 v[36:39], v[178:181], v[202:205], v[36:39]
	v_mfma_f32_16x16x32_bf16 v[32:35], v[186:189], v[202:205], v[32:35]
	v_mfma_f32_16x16x32_bf16 v[20:23], v[178:181], v[210:213], v[20:23]
	v_mfma_f32_16x16x32_bf16 v[16:19], v[186:189], v[210:213], v[16:19]
	v_mfma_f32_16x16x32_bf16 v[4:7], v[178:181], v[218:221], v[4:7]
	v_mfma_f32_16x16x32_bf16 v[0:3], v[186:189], v[218:221], v[0:3]
	s_setprio 1
	s_barrier
	s_add_i32 s57, 0, 0x18000
	s_add_i32 s58, 0, 0x1c000
	v_add_u32_e32 v170, s57, v146
	v_add_u32_e32 v186, s58, v146
	ds_read_b128 v[158:161], v170
	ds_read_b128 v[162:165], v170 offset:1024
	ds_read_b128 v[166:169], v170 offset:2048
	ds_read_b128 v[170:173], v170 offset:3072
	ds_read_b128 v[174:177], v186
	ds_read_b128 v[178:181], v186 offset:1024
	ds_read_b128 v[182:185], v186 offset:2048
	ds_read_b128 v[186:189], v186 offset:3072
	s_add_u32 s48, s48, 0x80000
	s_addc_u32 s49, s49, 0
	s_mov_b32 m0, s16
	v_lshl_add_u64 v[228:229], s[48:49], 0, v[128:129]
	ds_read_b128 v[190:193], v157 offset:32768
	ds_read_b128 v[194:197], v157 offset:33792
	ds_read_b128 v[198:201], v157 offset:34816
	ds_read_b128 v[202:205], v157 offset:35840
	ds_read_b128 v[206:209], v157 offset:36864
	ds_read_b128 v[210:213], v157 offset:37888
	ds_read_b128 v[214:217], v157 offset:38912
	ds_read_b128 v[218:221], v157 offset:39936
	global_load_lds_dwordx4 v[228:229], off
	v_lshl_add_u64 v[228:229], s[48:49], 0, v[132:133]
	s_mov_b32 m0, s17
	s_nop 0
	global_load_lds_dwordx4 v[228:229], off
	s_waitcnt vmcnt(8)
	s_waitcnt lgkmcnt(0)
	s_barrier
	s_setprio 0
	s_waitcnt lgkmcnt(0)
	v_mfma_f32_16x16x32_bf16 v[124:127], v[158:161], v[190:193], v[124:127]
	v_mfma_f32_16x16x32_bf16 v[120:123], v[166:169], v[190:193], v[120:123]
	v_mfma_f32_16x16x32_bf16 v[108:111], v[158:161], v[198:201], v[108:111]
	v_mfma_f32_16x16x32_bf16 v[104:107], v[166:169], v[198:201], v[104:107]
	v_mfma_f32_16x16x32_bf16 v[92:95], v[158:161], v[206:209], v[92:95]
	v_mfma_f32_16x16x32_bf16 v[88:91], v[166:169], v[206:209], v[88:91]
	v_mfma_f32_16x16x32_bf16 v[76:79], v[158:161], v[214:217], v[76:79]
	v_mfma_f32_16x16x32_bf16 v[72:75], v[166:169], v[214:217], v[72:75]
	v_mfma_f32_16x16x32_bf16 v[124:127], v[162:165], v[194:197], v[124:127]
	v_mfma_f32_16x16x32_bf16 v[120:123], v[170:173], v[194:197], v[120:123]
	v_mfma_f32_16x16x32_bf16 v[108:111], v[162:165], v[202:205], v[108:111]
	v_mfma_f32_16x16x32_bf16 v[104:107], v[170:173], v[202:205], v[104:107]
	v_mfma_f32_16x16x32_bf16 v[92:95], v[162:165], v[210:213], v[92:95]
	v_mfma_f32_16x16x32_bf16 v[88:91], v[170:173], v[210:213], v[88:91]
	v_mfma_f32_16x16x32_bf16 v[76:79], v[162:165], v[218:221], v[76:79]
	v_mfma_f32_16x16x32_bf16 v[72:75], v[170:173], v[218:221], v[72:75]
	v_mfma_f32_16x16x32_bf16 v[116:119], v[174:177], v[190:193], v[116:119]
	v_mfma_f32_16x16x32_bf16 v[112:115], v[182:185], v[190:193], v[112:115]
	v_mfma_f32_16x16x32_bf16 v[100:103], v[174:177], v[198:201], v[100:103]
	v_mfma_f32_16x16x32_bf16 v[96:99], v[182:185], v[198:201], v[96:99]
	v_mfma_f32_16x16x32_bf16 v[84:87], v[174:177], v[206:209], v[84:87]
	v_mfma_f32_16x16x32_bf16 v[80:83], v[182:185], v[206:209], v[80:83]
	v_mfma_f32_16x16x32_bf16 v[68:71], v[174:177], v[214:217], v[68:71]
	v_mfma_f32_16x16x32_bf16 v[64:67], v[182:185], v[214:217], v[64:67]
	v_mfma_f32_16x16x32_bf16 v[116:119], v[178:181], v[194:197], v[116:119]
	v_mfma_f32_16x16x32_bf16 v[112:115], v[186:189], v[194:197], v[112:115]
	v_mfma_f32_16x16x32_bf16 v[100:103], v[178:181], v[202:205], v[100:103]
	v_mfma_f32_16x16x32_bf16 v[96:99], v[186:189], v[202:205], v[96:99]
	v_mfma_f32_16x16x32_bf16 v[84:87], v[178:181], v[210:213], v[84:87]
	v_mfma_f32_16x16x32_bf16 v[80:83], v[186:189], v[210:213], v[80:83]
	v_mfma_f32_16x16x32_bf16 v[68:71], v[178:181], v[218:221], v[68:71]
	v_mfma_f32_16x16x32_bf16 v[64:67], v[186:189], v[218:221], v[64:67]
	s_setprio 1
	s_barrier
; #define PG8_STAGE(bufoff, gbase, voff) do { _Pragma("unroll") for (int _i = 0; _i < 2; ++_i) \
;         __builtin_amdgcn_global_load_lds((const unsigned*)((const char*)(gbase) + (voff)[_i]), (LAS unsigned*)(lds + (bufoff) + ldsw + _i * 8192), 16, 0, 0); } while (0)
; #define PG8_LDA(dst, b, h) do { _Pragma("unroll") for (int m = 0; m < 4; ++m) _Pragma("unroll") for (int k = 0; k < 2; ++k) dst[m][k] = *(const LAS bf16x8*)(lds + PG8_SA(b, h) + aoff + m * 2048 + k * 1024); } while (0)
; #define PG8_MMA(ai, bj, At, Bt) do { __builtin_amdgcn_s_setprio(1); _Pragma("unroll") for (int m = 0; m < 4; ++m) _Pragma("unroll") for (int n = 0; n < 2; ++n) _Pragma("unroll") for (int k = 0; k < 2; ++k) \
;         acc[ai][bj][m][n] = __builtin_amdgcn_mfma_f32_16x16x32_bf16(Bt[n][k], At[m][k], acc[ai][bj][m][n], 0, 0, 0); __builtin_amdgcn_s_setprio(0); } while (0)
; #define PG8_WAIT_V(n) asm volatile("s_waitcnt vmcnt(" #n ")" ::: "memory")
; #define PG8_WAIT_L(n) asm volatile("s_waitcnt lgkmcnt(" #n ")" ::: "memory")
; #define PG8_BAR __builtin_amdgcn_s_barrier()
; #define PG8_SCHED __builtin_amdgcn_sched_barrier(0)
; __device__ __forceinline__ void gemm_phase(LAS unsigned char* lds, const Params& p, const bf16_t* gA, const bf16_t* gBt, const int gM, const int gN, const int gK, const int epi, const int perm, bf16_t* const Hp, const int goff, const float coef) {
;     ...
;             PG8_LDA(At, 1, 1); PG8_STAGE(PG8_SB(1, 0), b3, voffB); PG8_STAGE(PG8_SB(1, 1), b3 + hstep, voffB); PG8_STAGE(PG8_SA(1, 0), a3, voffA);
;             PG8_WAIT_V(8); PG8_WAIT_L(0); PG8_BAR; PG8_MMA(1, 0, At, B0); PG8_MMA(1, 1, At, B1); PG8_BAR; PG8_SCHED;
;         }
;         if (wr == 0) PG8_BAR;
	s_add_i32 s48, s57, s11
	v_lshl_add_u64 v[144:145], v[144:145], 0, s[8:9]
	s_mov_b32 m0, s48
	ds_read_b128 v[190:193], v157 offset:49152
	ds_read_b128 v[194:197], v157 offset:50176
	ds_read_b128 v[198:201], v157 offset:51200
	ds_read_b128 v[202:205], v157 offset:52224
	ds_read_b128 v[206:209], v157 offset:53248
	ds_read_b128 v[210:213], v157 offset:54272
	ds_read_b128 v[214:217], v157 offset:55296
	ds_read_b128 v[218:221], v157 offset:56320
	global_load_lds_dwordx4 v[144:145], off
	s_add_i32 m0, s48, 0x2000
	s_add_u32 s46, s46, 0x80080
	v_lshl_add_u64 v[144:145], v[222:223], 0, s[8:9]
	s_addc_u32 s47, s47, 0
	s_add_i32 s48, s58, s11
	global_load_lds_dwordx4 v[144:145], off
	v_lshl_add_u64 v[144:145], s[46:47], 0, v[130:131]
	s_mov_b32 m0, s48
	s_nop 0
	global_load_lds_dwordx4 v[144:145], off
	v_lshl_add_u64 v[144:145], s[46:47], 0, v[134:135]
	s_add_i32 m0, s48, 0x2000
	s_nop 0
	global_load_lds_dwordx4 v[144:145], off
	v_lshl_add_u64 v[144:145], v[224:225], 0, s[8:9]
	s_mov_b32 m0, s19
	s_nop 0
	global_load_lds_dwordx4 v[144:145], off
	v_lshl_add_u64 v[144:145], v[226:227], 0, s[8:9]
	s_mov_b32 m0, s20
	s_nop 0
	global_load_lds_dwordx4 v[144:145], off
	s_waitcnt vmcnt(8)
	s_waitcnt lgkmcnt(0)
	s_barrier
	s_setprio 0
	s_waitcnt lgkmcnt(0)
	v_mfma_f32_16x16x32_bf16 v[60:63], v[158:161], v[190:193], v[60:63]
	v_mfma_f32_16x16x32_bf16 v[56:59], v[166:169], v[190:193], v[56:59]
	v_mfma_f32_16x16x32_bf16 v[44:47], v[158:161], v[198:201], v[44:47]
	v_mfma_f32_16x16x32_bf16 v[40:43], v[166:169], v[198:201], v[40:43]
	v_mfma_f32_16x16x32_bf16 v[28:31], v[158:161], v[206:209], v[28:31]
	v_mfma_f32_16x16x32_bf16 v[24:27], v[166:169], v[206:209], v[24:27]
	v_mfma_f32_16x16x32_bf16 v[12:15], v[158:161], v[214:217], v[12:15]
	v_mfma_f32_16x16x32_bf16 v[8:11], v[166:169], v[214:217], v[8:11]
	v_mfma_f32_16x16x32_bf16 v[60:63], v[162:165], v[194:197], v[60:63]
	v_mfma_f32_16x16x32_bf16 v[56:59], v[170:173], v[194:197], v[56:59]
	v_mfma_f32_16x16x32_bf16 v[44:47], v[162:165], v[202:205], v[44:47]
	v_mfma_f32_16x16x32_bf16 v[40:43], v[170:173], v[202:205], v[40:43]
	v_mfma_f32_16x16x32_bf16 v[28:31], v[162:165], v[210:213], v[28:31]
	v_mfma_f32_16x16x32_bf16 v[24:27], v[170:173], v[210:213], v[24:27]
	v_mfma_f32_16x16x32_bf16 v[12:15], v[162:165], v[218:221], v[12:15]
	v_mfma_f32_16x16x32_bf16 v[8:11], v[170:173], v[218:221], v[8:11]
	v_mfma_f32_16x16x32_bf16 v[52:55], v[174:177], v[190:193], v[52:55]
	v_mfma_f32_16x16x32_bf16 v[48:51], v[182:185], v[190:193], v[48:51]
	v_mfma_f32_16x16x32_bf16 v[36:39], v[174:177], v[198:201], v[36:39]
	v_mfma_f32_16x16x32_bf16 v[32:35], v[182:185], v[198:201], v[32:35]
	v_mfma_f32_16x16x32_bf16 v[20:23], v[174:177], v[206:209], v[20:23]
	v_mfma_f32_16x16x32_bf16 v[16:19], v[182:185], v[206:209], v[16:19]
	v_mfma_f32_16x16x32_bf16 v[4:7], v[174:177], v[214:217], v[4:7]
	v_mfma_f32_16x16x32_bf16 v[0:3], v[182:185], v[214:217], v[0:3]
	v_mfma_f32_16x16x32_bf16 v[52:55], v[178:181], v[194:197], v[52:55]
	v_mfma_f32_16x16x32_bf16 v[48:51], v[186:189], v[194:197], v[48:51]
	v_mfma_f32_16x16x32_bf16 v[36:39], v[178:181], v[202:205], v[36:39]
	v_mfma_f32_16x16x32_bf16 v[32:35], v[186:189], v[202:205], v[32:35]
	v_mfma_f32_16x16x32_bf16 v[20:23], v[178:181], v[210:213], v[20:23]
	v_mfma_f32_16x16x32_bf16 v[16:19], v[186:189], v[210:213], v[16:19]
	v_mfma_f32_16x16x32_bf16 v[4:7], v[178:181], v[218:221], v[4:7]
	v_mfma_f32_16x16x32_bf16 v[0:3], v[186:189], v[218:221], v[0:3]
	s_setprio 1
	s_barrier
	s_add_u32 s44, s44, 0x100
	s_addc_u32 s45, s45, 0
	s_add_u32 s54, s54, 0x100
	s_addc_u32 s55, s55, 0
	s_cmp_ge_u32 s56, s52
	s_mov_b32 s48, s56
	s_cbranch_scc0 .LBB0_170
	s_and_b64 vcc, exec, s[12:13]
	s_cbranch_vccz .LBB0_173
	s_barrier

; #define PG8_STAGE(bufoff, gbase, voff) do { _Pragma("unroll") for (int _i = 0; _i < 2; ++_i) \
;         __builtin_amdgcn_global_load_lds((const unsigned*)((const char*)(gbase) + (voff)[_i]), (LAS unsigned*)(lds + (bufoff) + ldsw + _i * 8192), 16, 0, 0); } while (0)
; #define PG8_LDA(dst, b, h) do { _Pragma("unroll") for (int m = 0; m < 4; ++m) _Pragma("unroll") for (int k = 0; k < 2; ++k) dst[m][k] = *(const LAS bf16x8*)(lds + PG8_SA(b, h) + aoff + m * 2048 + k * 1024); } while (0)
; #define PG8_LDB(dst, b, h) do { _Pragma("unroll") for (int n = 0; n < 2; ++n) _Pragma("unroll") for (int k = 0; k < 2; ++k) dst[n][k] = *(const LAS bf16x8*)(lds + PG8_SB(b, h) + boff + n * 2048 + k * 1024); } while (0)
; #define PG8_MMA(ai, bj, At, Bt) do { __builtin_amdgcn_s_setprio(1); _Pragma("unroll") for (int m = 0; m < 4; ++m) _Pragma("unroll") for (int n = 0; n < 2; ++n) _Pragma("unroll") for (int k = 0; k < 2; ++k) \
;         acc[ai][bj][m][n] = __builtin_amdgcn_mfma_f32_16x16x32_bf16(Bt[n][k], At[m][k], acc[ai][bj][m][n], 0, 0, 0); __builtin_amdgcn_s_setprio(0); } while (0)
; #define PG8_WAIT_V(n) asm volatile("s_waitcnt vmcnt(" #n ")" ::: "memory")
; #define PG8_WAIT_L(n) asm volatile("s_waitcnt lgkmcnt(" #n ")" ::: "memory")
; #define PG8_BAR __builtin_amdgcn_s_barrier()
; #define PG8_SCHED __builtin_amdgcn_sched_barrier(0)
; __device__ __forceinline__ void gemm_phase(LAS unsigned char* lds, const Params& p, const bf16_t* gA, const bf16_t* gBt, const int gM, const int gN, const int gK, const int epi, const int perm, bf16_t* const Hp, const int goff, const float coef) {
;     ...
;             const bool last = (t == nt - 2);
;             const char* a1 = cA + (size_t)(t + 1) * kstep;
;             const char* a2 = last ? nA : cA + (size_t)(t + 2) * kstep; const char* b2 = last ? nB : cB + (size_t)(t + 2) * kstep;
;             const char* a3 = a2 + kstep; const char* b3 = b2 + kstep;
;             PG8_LDB(B0, 0, 0); PG8_LDB(B1, 0, 1); PG8_SCHED; PG8_LDA(At, 0, 0); PG8_STAGE(PG8_SA(1, 1), a1 + hstep, voffA);
;             PG8_WAIT_V(8); PG8_WAIT_L(0); PG8_BAR; PG8_MMA(0, 0, At, B0); PG8_MMA(0, 1, At, B1); PG8_BAR; PG8_SCHED;
;             PG8_LDA(At, 0, 1); PG8_STAGE(PG8_SB(0, 0), b2, voffB); PG8_STAGE(PG8_SB(0, 1), b2 + hstep, voffB); PG8_STAGE(PG8_SA(0, 0), a2, voffA);
.LBB0_264:
	ds_read_b128 v[146:149], v167
	ds_read_b128 v[150:153], v167 offset:1024
	ds_read_b128 v[154:157], v167 offset:2048
	ds_read_b128 v[170:173], v167 offset:3072
	ds_read_b128 v[174:177], v168
	ds_read_b128 v[178:181], v168 offset:1024
	ds_read_b128 v[182:185], v168 offset:2048
	ds_read_b128 v[186:189], v168 offset:3072
	s_add_i32 s58, s34, 2
	s_add_u32 s35, s30, 0xffea0080
	s_addc_u32 s38, s31, -1
	s_cmp_eq_u32 s55, s34
	s_cselect_b32 s34, s28, s56
	s_cselect_b32 s39, s27, s38
	s_cselect_b32 s38, s26, s35
	s_cselect_b32 s35, s29, s57
	v_lshl_add_u64 v[222:223], s[30:31], 0, v[136:137]
	s_add_i32 m0, s17, 0xc000
	ds_read_b128 v[190:193], v169
	ds_read_b128 v[194:197], v169 offset:1024
	ds_read_b128 v[198:201], v169 offset:2048
	ds_read_b128 v[202:205], v169 offset:3072
	ds_read_b128 v[206:209], v169 offset:4096
	ds_read_b128 v[210:213], v169 offset:5120
	ds_read_b128 v[214:217], v169 offset:6144
	ds_read_b128 v[218:221], v169 offset:7168
	global_load_lds_dwordx4 v[222:223], off
	v_lshl_add_u64 v[222:223], s[30:31], 0, v[138:139]
	s_add_i32 m0, s17, 0xe000
	s_nop 0
	global_load_lds_dwordx4 v[222:223], off
	s_waitcnt vmcnt(8)
	s_waitcnt lgkmcnt(0)
	s_barrier
	s_setprio 0
	s_waitcnt lgkmcnt(0)
	v_mfma_f32_16x16x32_bf16 v[124:127], v[146:149], v[190:193], v[124:127]
	v_mfma_f32_16x16x32_bf16 v[120:123], v[154:157], v[190:193], v[120:123]
	v_mfma_f32_16x16x32_bf16 v[116:119], v[146:149], v[198:201], v[116:119]
	v_mfma_f32_16x16x32_bf16 v[112:115], v[154:157], v[198:201], v[112:115]
	v_mfma_f32_16x16x32_bf16 v[108:111], v[146:149], v[206:209], v[108:111]
	v_mfma_f32_16x16x32_bf16 v[104:107], v[154:157], v[206:209], v[104:107]
	v_mfma_f32_16x16x32_bf16 v[100:103], v[146:149], v[214:217], v[100:103]
	v_mfma_f32_16x16x32_bf16 v[96:99], v[154:157], v[214:217], v[96:99]
	v_mfma_f32_16x16x32_bf16 v[124:127], v[150:153], v[194:197], v[124:127]
	v_mfma_f32_16x16x32_bf16 v[120:123], v[170:173], v[194:197], v[120:123]
	v_mfma_f32_16x16x32_bf16 v[116:119], v[150:153], v[202:205], v[116:119]
	v_mfma_f32_16x16x32_bf16 v[112:115], v[170:173], v[202:205], v[112:115]
	v_mfma_f32_16x16x32_bf16 v[108:111], v[150:153], v[210:213], v[108:111]
	v_mfma_f32_16x16x32_bf16 v[104:107], v[170:173], v[210:213], v[104:107]
	v_mfma_f32_16x16x32_bf16 v[100:103], v[150:153], v[218:221], v[100:103]
	v_mfma_f32_16x16x32_bf16 v[96:99], v[170:173], v[218:221], v[96:99]
	v_mfma_f32_16x16x32_bf16 v[68:71], v[174:177], v[190:193], v[68:71]
	v_mfma_f32_16x16x32_bf16 v[60:63], v[182:185], v[190:193], v[60:63]
	v_mfma_f32_16x16x32_bf16 v[52:55], v[174:177], v[198:201], v[52:55]
	v_mfma_f32_16x16x32_bf16 v[48:51], v[182:185], v[198:201], v[48:51]
	v_mfma_f32_16x16x32_bf16 v[44:47], v[174:177], v[206:209], v[44:47]
	v_mfma_f32_16x16x32_bf16 v[40:43], v[182:185], v[206:209], v[40:43]
	v_mfma_f32_16x16x32_bf16 v[36:39], v[174:177], v[214:217], v[36:39]
	v_mfma_f32_16x16x32_bf16 v[32:35], v[182:185], v[214:217], v[32:35]
	v_mfma_f32_16x16x32_bf16 v[68:71], v[178:181], v[194:197], v[68:71]
	v_mfma_f32_16x16x32_bf16 v[60:63], v[186:189], v[194:197], v[60:63]
	v_mfma_f32_16x16x32_bf16 v[52:55], v[178:181], v[202:205], v[52:55]
	v_mfma_f32_16x16x32_bf16 v[48:51], v[186:189], v[202:205], v[48:51]
	v_mfma_f32_16x16x32_bf16 v[44:47], v[178:181], v[210:213], v[44:47]
	v_mfma_f32_16x16x32_bf16 v[40:43], v[186:189], v[210:213], v[40:43]
	v_mfma_f32_16x16x32_bf16 v[36:39], v[178:181], v[218:221], v[36:39]
	v_mfma_f32_16x16x32_bf16 v[32:35], v[186:189], v[218:221], v[32:35]
	s_setprio 1
	s_barrier
	s_add_i32 s59, s46, s16
	v_lshl_add_u64 v[222:223], s[34:35], 0, v[130:131]
	s_mov_b32 m0, s59
	ds_read_b128 v[190:193], v169 offset:16384
	ds_read_b128 v[194:197], v169 offset:17408
	ds_read_b128 v[198:201], v169 offset:18432
	ds_read_b128 v[202:205], v169 offset:19456
	ds_read_b128 v[206:209], v169 offset:20480
	ds_read_b128 v[210:213], v169 offset:21504
	ds_read_b128 v[214:217], v169 offset:22528
	ds_read_b128 v[218:221], v169 offset:23552
	global_load_lds_dwordx4 v[222:223], off
	s_add_i32 m0, s59, 0x2000
	s_add_u32 s60, s34, 0x160000
	v_lshl_add_u64 v[224:225], s[34:35], 0, v[134:135]
	s_addc_u32 s61, s35, 0
	s_add_i32 s59, s47, s16
	global_load_lds_dwordx4 v[224:225], off
	v_lshl_add_u64 v[226:227], s[60:61], 0, v[130:131]
	s_mov_b32 m0, s59
	v_lshl_add_u64 v[228:229], s[38:39], 0, v[132:133]
	global_load_lds_dwordx4 v[226:227], off
	v_lshl_add_u64 v[226:227], s[60:61], 0, v[134:135]
	s_add_i32 m0, s59, 0x2000
	s_nop 0
	global_load_lds_dwordx4 v[226:227], off
	v_lshl_add_u64 v[226:227], s[38:39], 0, v[128:129]
	s_mov_b32 m0, s17
	s_nop 0
	global_load_lds_dwordx4 v[226:227], off
	s_mov_b32 m0, s18
	s_nop 0
	global_load_lds_dwordx4 v[228:229], off
	s_waitcnt vmcnt(8)
	s_waitcnt lgkmcnt(0)
	s_barrier
; #define PG8_STAGE(bufoff, gbase, voff) do { _Pragma("unroll") for (int _i = 0; _i < 2; ++_i) \
;         __builtin_amdgcn_global_load_lds((const unsigned*)((const char*)(gbase) + (voff)[_i]), (LAS unsigned*)(lds + (bufoff) + ldsw + _i * 8192), 16, 0, 0); } while (0)
; #define PG8_LDA(dst, b, h) do { _Pragma("unroll") for (int m = 0; m < 4; ++m) _Pragma("unroll") for (int k = 0; k < 2; ++k) dst[m][k] = *(const LAS bf16x8*)(lds + PG8_SA(b, h) + aoff + m * 2048 + k * 1024); } while (0)
; #define PG8_LDB(dst, b, h) do { _Pragma("unroll") for (int n = 0; n < 2; ++n) _Pragma("unroll") for (int k = 0; k < 2; ++k) dst[n][k] = *(const LAS bf16x8*)(lds + PG8_SB(b, h) + boff + n * 2048 + k * 1024); } while (0)
; #define PG8_MMA(ai, bj, At, Bt) do { __builtin_amdgcn_s_setprio(1); _Pragma("unroll") for (int m = 0; m < 4; ++m) _Pragma("unroll") for (int n = 0; n < 2; ++n) _Pragma("unroll") for (int k = 0; k < 2; ++k) \
;         acc[ai][bj][m][n] = __builtin_amdgcn_mfma_f32_16x16x32_bf16(Bt[n][k], At[m][k], acc[ai][bj][m][n], 0, 0, 0); __builtin_amdgcn_s_setprio(0); } while (0)
; #define PG8_WAIT_V(n) asm volatile("s_waitcnt vmcnt(" #n ")" ::: "memory")
; #define PG8_WAIT_L(n) asm volatile("s_waitcnt lgkmcnt(" #n ")" ::: "memory")
; #define PG8_BAR __builtin_amdgcn_s_barrier()
; #define PG8_SCHED __builtin_amdgcn_sched_barrier(0)
; __device__ __forceinline__ void gemm_phase(LAS unsigned char* lds, const Params& p, const bf16_t* gA, const bf16_t* gBt, const int gM, const int gN, const int gK, const int epi, const int perm, bf16_t* const Hp, const int goff, const float coef) {
;     ...
;             PG8_WAIT_V(8); PG8_WAIT_L(0); PG8_BAR; PG8_MMA(1, 0, At, B0); PG8_MMA(1, 1, At, B1); PG8_BAR; PG8_SCHED;
;             PG8_LDB(B0, 1, 0); PG8_LDB(B1, 1, 1); PG8_SCHED; PG8_LDA(At, 1, 0); PG8_STAGE(PG8_SA(0, 1), a2 + hstep, voffA);
;             PG8_WAIT_V(8); PG8_WAIT_L(0); PG8_BAR; PG8_MMA(0, 0, At, B0); PG8_MMA(0, 1, At, B1); PG8_BAR; PG8_SCHED;
	s_setprio 0
	s_waitcnt lgkmcnt(0)
	v_mfma_f32_16x16x32_bf16 v[92:95], v[146:149], v[190:193], v[92:95]
	v_mfma_f32_16x16x32_bf16 v[88:91], v[154:157], v[190:193], v[88:91]
	v_mfma_f32_16x16x32_bf16 v[84:87], v[146:149], v[198:201], v[84:87]
	v_mfma_f32_16x16x32_bf16 v[80:83], v[154:157], v[198:201], v[80:83]
	v_mfma_f32_16x16x32_bf16 v[76:79], v[146:149], v[206:209], v[76:79]
	v_mfma_f32_16x16x32_bf16 v[72:75], v[154:157], v[206:209], v[72:75]
	v_mfma_f32_16x16x32_bf16 v[64:67], v[146:149], v[214:217], v[64:67]
	v_mfma_f32_16x16x32_bf16 v[56:59], v[154:157], v[214:217], v[56:59]
	v_mfma_f32_16x16x32_bf16 v[92:95], v[150:153], v[194:197], v[92:95]
	v_mfma_f32_16x16x32_bf16 v[88:91], v[170:173], v[194:197], v[88:91]
	v_mfma_f32_16x16x32_bf16 v[84:87], v[150:153], v[202:205], v[84:87]
	v_mfma_f32_16x16x32_bf16 v[80:83], v[170:173], v[202:205], v[80:83]
	v_mfma_f32_16x16x32_bf16 v[76:79], v[150:153], v[210:213], v[76:79]
	v_mfma_f32_16x16x32_bf16 v[72:75], v[170:173], v[210:213], v[72:75]
	v_mfma_f32_16x16x32_bf16 v[64:67], v[150:153], v[218:221], v[64:67]
	v_mfma_f32_16x16x32_bf16 v[56:59], v[170:173], v[218:221], v[56:59]
	v_mfma_f32_16x16x32_bf16 v[28:31], v[174:177], v[190:193], v[28:31]
	v_mfma_f32_16x16x32_bf16 v[24:27], v[182:185], v[190:193], v[24:27]
	v_mfma_f32_16x16x32_bf16 v[20:23], v[174:177], v[198:201], v[20:23]
	v_mfma_f32_16x16x32_bf16 v[16:19], v[182:185], v[198:201], v[16:19]
	v_mfma_f32_16x16x32_bf16 v[12:15], v[174:177], v[206:209], v[12:15]
	v_mfma_f32_16x16x32_bf16 v[8:11], v[182:185], v[206:209], v[8:11]
	v_mfma_f32_16x16x32_bf16 v[4:7], v[174:177], v[214:217], v[4:7]
	v_mfma_f32_16x16x32_bf16 v[0:3], v[182:185], v[214:217], v[0:3]
	v_mfma_f32_16x16x32_bf16 v[28:31], v[178:181], v[194:197], v[28:31]
	v_mfma_f32_16x16x32_bf16 v[24:27], v[186:189], v[194:197], v[24:27]
	v_mfma_f32_16x16x32_bf16 v[20:23], v[178:181], v[202:205], v[20:23]
	v_mfma_f32_16x16x32_bf16 v[16:19], v[186:189], v[202:205], v[16:19]
	v_mfma_f32_16x16x32_bf16 v[12:15], v[178:181], v[210:213], v[12:15]
	v_mfma_f32_16x16x32_bf16 v[8:11], v[186:189], v[210:213], v[8:11]
	v_mfma_f32_16x16x32_bf16 v[4:7], v[178:181], v[218:221], v[4:7]
	v_mfma_f32_16x16x32_bf16 v[0:3], v[186:189], v[218:221], v[0:3]
	s_setprio 1
	s_barrier
	s_add_i32 s59, 0, 0x18000
	s_add_i32 s60, 0, 0x1c000
	v_add_u32_e32 v170, s59, v158
	v_add_u32_e32 v186, s60, v158
	ds_read_b128 v[146:149], v170
	ds_read_b128 v[150:153], v170 offset:1024
	ds_read_b128 v[154:157], v170 offset:2048
	ds_read_b128 v[170:173], v170 offset:3072
	ds_read_b128 v[174:177], v186
	ds_read_b128 v[178:181], v186 offset:1024
	ds_read_b128 v[182:185], v186 offset:2048
	ds_read_b128 v[186:189], v186 offset:3072
	s_add_u32 s38, s38, 0x160000
	s_addc_u32 s39, s39, 0
	s_mov_b32 m0, s19
	v_lshl_add_u64 v[230:231], s[38:39], 0, v[128:129]
	ds_read_b128 v[190:193], v169 offset:32768
	ds_read_b128 v[194:197], v169 offset:33792
	ds_read_b128 v[198:201], v169 offset:34816
	ds_read_b128 v[202:205], v169 offset:35840
	ds_read_b128 v[206:209], v169 offset:36864
	ds_read_b128 v[210:213], v169 offset:37888
	ds_read_b128 v[214:217], v169 offset:38912
	ds_read_b128 v[218:221], v169 offset:39936
	global_load_lds_dwordx4 v[230:231], off
	v_lshl_add_u64 v[230:231], s[38:39], 0, v[132:133]
	s_mov_b32 m0, s20
	s_nop 0
	global_load_lds_dwordx4 v[230:231], off
	s_waitcnt vmcnt(8)
	s_waitcnt lgkmcnt(0)
	s_barrier
	s_setprio 0
	s_waitcnt lgkmcnt(0)
	v_mfma_f32_16x16x32_bf16 v[124:127], v[146:149], v[190:193], v[124:127]
	v_mfma_f32_16x16x32_bf16 v[120:123], v[154:157], v[190:193], v[120:123]
	v_mfma_f32_16x16x32_bf16 v[116:119], v[146:149], v[198:201], v[116:119]
	v_mfma_f32_16x16x32_bf16 v[112:115], v[154:157], v[198:201], v[112:115]
	v_mfma_f32_16x16x32_bf16 v[108:111], v[146:149], v[206:209], v[108:111]
	v_mfma_f32_16x16x32_bf16 v[104:107], v[154:157], v[206:209], v[104:107]
	v_mfma_f32_16x16x32_bf16 v[100:103], v[146:149], v[214:217], v[100:103]
	v_mfma_f32_16x16x32_bf16 v[96:99], v[154:157], v[214:217], v[96:99]
	v_mfma_f32_16x16x32_bf16 v[124:127], v[150:153], v[194:197], v[124:127]
	v_mfma_f32_16x16x32_bf16 v[120:123], v[170:173], v[194:197], v[120:123]
	v_mfma_f32_16x16x32_bf16 v[116:119], v[150:153], v[202:205], v[116:119]
	v_mfma_f32_16x16x32_bf16 v[112:115], v[170:173], v[202:205], v[112:115]
	v_mfma_f32_16x16x32_bf16 v[108:111], v[150:153], v[210:213], v[108:111]
	v_mfma_f32_16x16x32_bf16 v[104:107], v[170:173], v[210:213], v[104:107]
	v_mfma_f32_16x16x32_bf16 v[100:103], v[150:153], v[218:221], v[100:103]
	v_mfma_f32_16x16x32_bf16 v[96:99], v[170:173], v[218:221], v[96:99]
	v_mfma_f32_16x16x32_bf16 v[68:71], v[174:177], v[190:193], v[68:71]
	v_mfma_f32_16x16x32_bf16 v[60:63], v[182:185], v[190:193], v[60:63]
	v_mfma_f32_16x16x32_bf16 v[52:55], v[174:177], v[198:201], v[52:55]
	v_mfma_f32_16x16x32_bf16 v[48:51], v[182:185], v[198:201], v[48:51]
	v_mfma_f32_16x16x32_bf16 v[44:47], v[174:177], v[206:209], v[44:47]
	v_mfma_f32_16x16x32_bf16 v[40:43], v[182:185], v[206:209], v[40:43]
	v_mfma_f32_16x16x32_bf16 v[36:39], v[174:177], v[214:217], v[36:39]
	v_mfma_f32_16x16x32_bf16 v[32:35], v[182:185], v[214:217], v[32:35]
	v_mfma_f32_16x16x32_bf16 v[68:71], v[178:181], v[194:197], v[68:71]
	v_mfma_f32_16x16x32_bf16 v[60:63], v[186:189], v[194:197], v[60:63]
	v_mfma_f32_16x16x32_bf16 v[52:55], v[178:181], v[202:205], v[52:55]
	v_mfma_f32_16x16x32_bf16 v[48:51], v[186:189], v[202:205], v[48:51]
	v_mfma_f32_16x16x32_bf16 v[44:47], v[178:181], v[210:213], v[44:47]
	v_mfma_f32_16x16x32_bf16 v[40:43], v[186:189], v[210:213], v[40:43]
	v_mfma_f32_16x16x32_bf16 v[36:39], v[178:181], v[218:221], v[36:39]
	v_mfma_f32_16x16x32_bf16 v[32:35], v[186:189], v[218:221], v[32:35]
	s_setprio 1
	s_barrier
; #define PG8_STAGE(bufoff, gbase, voff) do { _Pragma("unroll") for (int _i = 0; _i < 2; ++_i) \
;         __builtin_amdgcn_global_load_lds((const unsigned*)((const char*)(gbase) + (voff)[_i]), (LAS unsigned*)(lds + (bufoff) + ldsw + _i * 8192), 16, 0, 0); } while (0)
; #define PG8_LDA(dst, b, h) do { _Pragma("unroll") for (int m = 0; m < 4; ++m) _Pragma("unroll") for (int k = 0; k < 2; ++k) dst[m][k] = *(const LAS bf16x8*)(lds + PG8_SA(b, h) + aoff + m * 2048 + k * 1024); } while (0)
; #define PG8_MMA(ai, bj, At, Bt) do { __builtin_amdgcn_s_setprio(1); _Pragma("unroll") for (int m = 0; m < 4; ++m) _Pragma("unroll") for (int n = 0; n < 2; ++n) _Pragma("unroll") for (int k = 0; k < 2; ++k) \
;         acc[ai][bj][m][n] = __builtin_amdgcn_mfma_f32_16x16x32_bf16(Bt[n][k], At[m][k], acc[ai][bj][m][n], 0, 0, 0); __builtin_amdgcn_s_setprio(0); } while (0)
; #define PG8_WAIT_V(n) asm volatile("s_waitcnt vmcnt(" #n ")" ::: "memory")
; #define PG8_WAIT_L(n) asm volatile("s_waitcnt lgkmcnt(" #n ")" ::: "memory")
; #define PG8_BAR __builtin_amdgcn_s_barrier()
; #define PG8_SCHED __builtin_amdgcn_sched_barrier(0)
; __device__ __forceinline__ void gemm_phase(LAS unsigned char* lds, const Params& p, const bf16_t* gA, const bf16_t* gBt, const int gM, const int gN, const int gK, const int epi, const int perm, bf16_t* const Hp, const int goff, const float coef) {
;     ...
;             PG8_LDA(At, 1, 1); PG8_STAGE(PG8_SB(1, 0), b3, voffB); PG8_STAGE(PG8_SB(1, 1), b3 + hstep, voffB); PG8_STAGE(PG8_SA(1, 0), a3, voffA);
;             PG8_WAIT_V(8); PG8_WAIT_L(0); PG8_BAR; PG8_MMA(1, 0, At, B0); PG8_MMA(1, 1, At, B1); PG8_BAR; PG8_SCHED;
;         }
;         if (wr == 0) PG8_BAR;
	s_add_i32 s38, s59, s16
	v_lshl_add_u64 v[222:223], v[222:223], 0, s[12:13]
	s_mov_b32 m0, s38
	ds_read_b128 v[190:193], v169 offset:49152
	ds_read_b128 v[194:197], v169 offset:50176
	ds_read_b128 v[198:201], v169 offset:51200
	ds_read_b128 v[202:205], v169 offset:52224
	ds_read_b128 v[206:209], v169 offset:53248
	ds_read_b128 v[210:213], v169 offset:54272
	ds_read_b128 v[214:217], v169 offset:55296
	ds_read_b128 v[218:221], v169 offset:56320
	global_load_lds_dwordx4 v[222:223], off
	s_add_i32 m0, s38, 0x2000
	s_add_u32 s34, s34, 0x160080
	v_lshl_add_u64 v[222:223], v[224:225], 0, s[12:13]
	s_addc_u32 s35, s35, 0
	s_add_i32 s38, s60, s16
	global_load_lds_dwordx4 v[222:223], off
	v_lshl_add_u64 v[222:223], s[34:35], 0, v[130:131]
	s_mov_b32 m0, s38
	s_nop 0
	global_load_lds_dwordx4 v[222:223], off
	v_lshl_add_u64 v[222:223], s[34:35], 0, v[134:135]
	s_add_i32 m0, s38, 0x2000
	s_nop 0
	global_load_lds_dwordx4 v[222:223], off
	v_lshl_add_u64 v[222:223], v[226:227], 0, s[12:13]
	s_mov_b32 m0, s23
	s_nop 0
	global_load_lds_dwordx4 v[222:223], off
	v_lshl_add_u64 v[222:223], v[228:229], 0, s[12:13]
	s_mov_b32 m0, s33
	s_nop 0
	global_load_lds_dwordx4 v[222:223], off
	s_waitcnt vmcnt(8)
	s_waitcnt lgkmcnt(0)
	s_barrier
	s_setprio 0
	s_waitcnt lgkmcnt(0)
	v_mfma_f32_16x16x32_bf16 v[92:95], v[146:149], v[190:193], v[92:95]
	v_mfma_f32_16x16x32_bf16 v[88:91], v[154:157], v[190:193], v[88:91]
	v_mfma_f32_16x16x32_bf16 v[84:87], v[146:149], v[198:201], v[84:87]
	v_mfma_f32_16x16x32_bf16 v[80:83], v[154:157], v[198:201], v[80:83]
	v_mfma_f32_16x16x32_bf16 v[76:79], v[146:149], v[206:209], v[76:79]
	v_mfma_f32_16x16x32_bf16 v[72:75], v[154:157], v[206:209], v[72:75]
	v_mfma_f32_16x16x32_bf16 v[64:67], v[146:149], v[214:217], v[64:67]
	v_mfma_f32_16x16x32_bf16 v[56:59], v[154:157], v[214:217], v[56:59]
	v_mfma_f32_16x16x32_bf16 v[92:95], v[150:153], v[194:197], v[92:95]
	v_mfma_f32_16x16x32_bf16 v[88:91], v[170:173], v[194:197], v[88:91]
	v_mfma_f32_16x16x32_bf16 v[84:87], v[150:153], v[202:205], v[84:87]
	v_mfma_f32_16x16x32_bf16 v[80:83], v[170:173], v[202:205], v[80:83]
	v_mfma_f32_16x16x32_bf16 v[76:79], v[150:153], v[210:213], v[76:79]
	v_mfma_f32_16x16x32_bf16 v[72:75], v[170:173], v[210:213], v[72:75]
	v_mfma_f32_16x16x32_bf16 v[64:67], v[150:153], v[218:221], v[64:67]
	v_mfma_f32_16x16x32_bf16 v[56:59], v[170:173], v[218:221], v[56:59]
	v_mfma_f32_16x16x32_bf16 v[28:31], v[174:177], v[190:193], v[28:31]
	v_mfma_f32_16x16x32_bf16 v[24:27], v[182:185], v[190:193], v[24:27]
	v_mfma_f32_16x16x32_bf16 v[20:23], v[174:177], v[198:201], v[20:23]
	v_mfma_f32_16x16x32_bf16 v[16:19], v[182:185], v[198:201], v[16:19]
	v_mfma_f32_16x16x32_bf16 v[12:15], v[174:177], v[206:209], v[12:15]
	v_mfma_f32_16x16x32_bf16 v[8:11], v[182:185], v[206:209], v[8:11]
	v_mfma_f32_16x16x32_bf16 v[4:7], v[174:177], v[214:217], v[4:7]
	v_mfma_f32_16x16x32_bf16 v[0:3], v[182:185], v[214:217], v[0:3]
	v_mfma_f32_16x16x32_bf16 v[28:31], v[178:181], v[194:197], v[28:31]
	v_mfma_f32_16x16x32_bf16 v[24:27], v[186:189], v[194:197], v[24:27]
	v_mfma_f32_16x16x32_bf16 v[20:23], v[178:181], v[202:205], v[20:23]
	v_mfma_f32_16x16x32_bf16 v[16:19], v[186:189], v[202:205], v[16:19]
	v_mfma_f32_16x16x32_bf16 v[12:15], v[178:181], v[210:213], v[12:15]
	v_mfma_f32_16x16x32_bf16 v[8:11], v[186:189], v[210:213], v[8:11]
	v_mfma_f32_16x16x32_bf16 v[4:7], v[178:181], v[218:221], v[4:7]
	v_mfma_f32_16x16x32_bf16 v[0:3], v[186:189], v[218:221], v[0:3]
	s_setprio 1
	s_barrier
	s_add_u32 s30, s30, 0x100
	s_addc_u32 s31, s31, 0
	s_add_u32 s56, s56, 0x100
	s_addc_u32 s57, s57, 0
	s_cmp_ge_u32 s58, s54
	s_mov_b32 s34, s58
	s_cbranch_scc0 .LBB0_264
	s_and_b64 vcc, exec, s[24:25]
	s_cbranch_vccz .LBB0_267
	s_barrier

; #define PG8_STAGE(bufoff, gbase, voff) do { _Pragma("unroll") for (int _i = 0; _i < 2; ++_i) \
;         __builtin_amdgcn_global_load_lds((const unsigned*)((const char*)(gbase) + (voff)[_i]), (LAS unsigned*)(lds + (bufoff) + ldsw + _i * 8192), 16, 0, 0); } while (0)
; #define PG8_LDA(dst, b, h) do { _Pragma("unroll") for (int m = 0; m < 4; ++m) _Pragma("unroll") for (int k = 0; k < 2; ++k) dst[m][k] = *(const LAS bf16x8*)(lds + PG8_SA(b, h) + aoff + m * 2048 + k * 1024); } while (0)
; #define PG8_LDB(dst, b, h) do { _Pragma("unroll") for (int n = 0; n < 2; ++n) _Pragma("unroll") for (int k = 0; k < 2; ++k) dst[n][k] = *(const LAS bf16x8*)(lds + PG8_SB(b, h) + boff + n * 2048 + k * 1024); } while (0)
; #define PG8_MMA(ai, bj, At, Bt) do { __builtin_amdgcn_s_setprio(1); _Pragma("unroll") for (int m = 0; m < 4; ++m) _Pragma("unroll") for (int n = 0; n < 2; ++n) _Pragma("unroll") for (int k = 0; k < 2; ++k) \
;         acc[ai][bj][m][n] = __builtin_amdgcn_mfma_f32_16x16x32_bf16(Bt[n][k], At[m][k], acc[ai][bj][m][n], 0, 0, 0); __builtin_amdgcn_s_setprio(0); } while (0)
; #define PG8_WAIT_V(n) asm volatile("s_waitcnt vmcnt(" #n ")" ::: "memory")
; #define PG8_WAIT_L(n) asm volatile("s_waitcnt lgkmcnt(" #n ")" ::: "memory")
; #define PG8_BAR __builtin_amdgcn_s_barrier()
; #define PG8_SCHED __builtin_amdgcn_sched_barrier(0)
; __device__ __forceinline__ void gemm_phase(LAS unsigned char* lds, const Params& p, const bf16_t* gA, const bf16_t* gBt, const int gM, const int gN, const int gK, const int epi, const int perm, bf16_t* const Hp, const int goff, const float coef) {
;     ...
;             const bool last = (t == nt - 2);
;             const char* a1 = cA + (size_t)(t + 1) * kstep;
;             const char* a2 = last ? nA : cA + (size_t)(t + 2) * kstep; const char* b2 = last ? nB : cB + (size_t)(t + 2) * kstep;
;             const char* a3 = a2 + kstep; const char* b3 = b2 + kstep;
;             PG8_LDB(B0, 0, 0); PG8_LDB(B1, 0, 1); PG8_SCHED; PG8_LDA(At, 0, 0); PG8_STAGE(PG8_SA(1, 1), a1 + hstep, voffA);
;             PG8_WAIT_V(8); PG8_WAIT_L(0); PG8_BAR; PG8_MMA(0, 0, At, B0); PG8_MMA(0, 1, At, B1); PG8_BAR; PG8_SCHED;
;             PG8_LDA(At, 0, 1); PG8_STAGE(PG8_SB(0, 0), b2, voffB); PG8_STAGE(PG8_SB(0, 1), b2 + hstep, voffB); PG8_STAGE(PG8_SA(0, 0), a2, voffA);
.LBB0_436:
	ds_read_b128 v[128:131], v180
	ds_read_b128 v[132:135], v180 offset:1024
	ds_read_b128 v[136:139], v180 offset:2048
	ds_read_b128 v[184:187], v180 offset:3072
	ds_read_b128 v[188:191], v181
	ds_read_b128 v[192:195], v181 offset:1024
	ds_read_b128 v[196:199], v181 offset:2048
	ds_read_b128 v[200:203], v181 offset:3072
	s_add_i32 s37, s45, 2
	s_add_u32 s4, s0, 0xfff80080
	s_addc_u32 s5, s1, -1
	s_cmp_eq_u32 s23, s45
	s_cselect_b32 s49, s14, s5
	s_cselect_b32 s48, s15, s4
	s_cselect_b32 s5, s16, s35
	s_cselect_b32 s4, s17, s33
	v_lshl_add_u64 v[168:169], s[0:1], 0, v[160:161]
	s_add_i32 m0, s47, 0xc000
	ds_read_b128 v[204:207], v182
	ds_read_b128 v[208:211], v182 offset:1024
	ds_read_b128 v[212:215], v182 offset:2048
	ds_read_b128 v[216:219], v182 offset:3072
	ds_read_b128 v[220:223], v182 offset:4096
	ds_read_b128 v[224:227], v182 offset:5120
	ds_read_b128 v[228:231], v182 offset:6144
	ds_read_b128 v[232:235], v182 offset:7168
	global_load_lds_dwordx4 v[168:169], off
	v_lshl_add_u64 v[168:169], s[0:1], 0, v[162:163]
	s_add_i32 m0, s47, 0xe000
	s_nop 0
	global_load_lds_dwordx4 v[168:169], off
	s_waitcnt vmcnt(8)
	s_waitcnt lgkmcnt(0)
	s_barrier
	s_setprio 0
	s_waitcnt lgkmcnt(0)
	v_mfma_f32_16x16x32_bf16 v[124:127], v[128:131], v[204:207], v[124:127]
	v_mfma_f32_16x16x32_bf16 v[120:123], v[136:139], v[204:207], v[120:123]
	v_mfma_f32_16x16x32_bf16 v[108:111], v[128:131], v[212:215], v[108:111]
	v_mfma_f32_16x16x32_bf16 v[104:107], v[136:139], v[212:215], v[104:107]
	v_mfma_f32_16x16x32_bf16 v[92:95], v[128:131], v[220:223], v[92:95]
	v_mfma_f32_16x16x32_bf16 v[88:91], v[136:139], v[220:223], v[88:91]
	v_mfma_f32_16x16x32_bf16 v[76:79], v[128:131], v[228:231], v[76:79]
	v_mfma_f32_16x16x32_bf16 v[72:75], v[136:139], v[228:231], v[72:75]
	v_mfma_f32_16x16x32_bf16 v[124:127], v[132:135], v[208:211], v[124:127]
	v_mfma_f32_16x16x32_bf16 v[120:123], v[184:187], v[208:211], v[120:123]
	v_mfma_f32_16x16x32_bf16 v[108:111], v[132:135], v[216:219], v[108:111]
	v_mfma_f32_16x16x32_bf16 v[104:107], v[184:187], v[216:219], v[104:107]
	v_mfma_f32_16x16x32_bf16 v[92:95], v[132:135], v[224:227], v[92:95]
	v_mfma_f32_16x16x32_bf16 v[88:91], v[184:187], v[224:227], v[88:91]
	v_mfma_f32_16x16x32_bf16 v[76:79], v[132:135], v[232:235], v[76:79]
	v_mfma_f32_16x16x32_bf16 v[72:75], v[184:187], v[232:235], v[72:75]
	v_mfma_f32_16x16x32_bf16 v[116:119], v[188:191], v[204:207], v[116:119]
	v_mfma_f32_16x16x32_bf16 v[112:115], v[196:199], v[204:207], v[112:115]
	v_mfma_f32_16x16x32_bf16 v[100:103], v[188:191], v[212:215], v[100:103]
	v_mfma_f32_16x16x32_bf16 v[96:99], v[196:199], v[212:215], v[96:99]
	v_mfma_f32_16x16x32_bf16 v[84:87], v[188:191], v[220:223], v[84:87]
	v_mfma_f32_16x16x32_bf16 v[80:83], v[196:199], v[220:223], v[80:83]
	v_mfma_f32_16x16x32_bf16 v[68:71], v[188:191], v[228:231], v[68:71]
	v_mfma_f32_16x16x32_bf16 v[64:67], v[196:199], v[228:231], v[64:67]
	v_mfma_f32_16x16x32_bf16 v[116:119], v[192:195], v[208:211], v[116:119]
	v_mfma_f32_16x16x32_bf16 v[112:115], v[200:203], v[208:211], v[112:115]
	v_mfma_f32_16x16x32_bf16 v[100:103], v[192:195], v[216:219], v[100:103]
	v_mfma_f32_16x16x32_bf16 v[96:99], v[200:203], v[216:219], v[96:99]
	v_mfma_f32_16x16x32_bf16 v[84:87], v[192:195], v[224:227], v[84:87]
	v_mfma_f32_16x16x32_bf16 v[80:83], v[200:203], v[224:227], v[80:83]
	v_mfma_f32_16x16x32_bf16 v[68:71], v[192:195], v[232:235], v[68:71]
	v_mfma_f32_16x16x32_bf16 v[64:67], v[200:203], v[232:235], v[64:67]
	s_setprio 1
	s_barrier
	s_add_i32 s45, s19, s52
	v_lshl_add_u64 v[168:169], s[4:5], 0, v[144:145]
	s_mov_b32 m0, s45
	ds_read_b128 v[204:207], v182 offset:16384
	ds_read_b128 v[208:211], v182 offset:17408
	ds_read_b128 v[212:215], v182 offset:18432
	ds_read_b128 v[216:219], v182 offset:19456
	ds_read_b128 v[220:223], v182 offset:20480
	ds_read_b128 v[224:227], v182 offset:21504
	ds_read_b128 v[228:231], v182 offset:22528
	ds_read_b128 v[232:235], v182 offset:23552
	global_load_lds_dwordx4 v[168:169], off
	s_add_i32 m0, s45, 0x2000
	s_add_u32 s50, s4, 0x80000
	v_lshl_add_u64 v[236:237], s[4:5], 0, v[148:149]
	s_addc_u32 s51, s5, 0
	s_add_i32 s45, s21, s52
	global_load_lds_dwordx4 v[236:237], off
	v_lshl_add_u64 v[238:239], s[50:51], 0, v[144:145]
	s_mov_b32 m0, s45
	v_lshl_add_u64 v[240:241], s[48:49], 0, v[146:147]
	global_load_lds_dwordx4 v[238:239], off
	v_lshl_add_u64 v[238:239], s[50:51], 0, v[148:149]
	s_add_i32 m0, s45, 0x2000
	s_nop 0
	global_load_lds_dwordx4 v[238:239], off
	v_lshl_add_u64 v[238:239], s[48:49], 0, v[142:143]
	s_mov_b32 m0, s47
	s_nop 0
	global_load_lds_dwordx4 v[238:239], off
	s_mov_b32 m0, s53
	s_nop 0
	global_load_lds_dwordx4 v[240:241], off
	s_waitcnt vmcnt(8)
	s_waitcnt lgkmcnt(0)
	s_barrier
; #define PG8_STAGE(bufoff, gbase, voff) do { _Pragma("unroll") for (int _i = 0; _i < 2; ++_i) \
;         __builtin_amdgcn_global_load_lds((const unsigned*)((const char*)(gbase) + (voff)[_i]), (LAS unsigned*)(lds + (bufoff) + ldsw + _i * 8192), 16, 0, 0); } while (0)
; #define PG8_LDA(dst, b, h) do { _Pragma("unroll") for (int m = 0; m < 4; ++m) _Pragma("unroll") for (int k = 0; k < 2; ++k) dst[m][k] = *(const LAS bf16x8*)(lds + PG8_SA(b, h) + aoff + m * 2048 + k * 1024); } while (0)
; #define PG8_LDB(dst, b, h) do { _Pragma("unroll") for (int n = 0; n < 2; ++n) _Pragma("unroll") for (int k = 0; k < 2; ++k) dst[n][k] = *(const LAS bf16x8*)(lds + PG8_SB(b, h) + boff + n * 2048 + k * 1024); } while (0)
; #define PG8_MMA(ai, bj, At, Bt) do { __builtin_amdgcn_s_setprio(1); _Pragma("unroll") for (int m = 0; m < 4; ++m) _Pragma("unroll") for (int n = 0; n < 2; ++n) _Pragma("unroll") for (int k = 0; k < 2; ++k) \
;         acc[ai][bj][m][n] = __builtin_amdgcn_mfma_f32_16x16x32_bf16(Bt[n][k], At[m][k], acc[ai][bj][m][n], 0, 0, 0); __builtin_amdgcn_s_setprio(0); } while (0)
; #define PG8_WAIT_V(n) asm volatile("s_waitcnt vmcnt(" #n ")" ::: "memory")
; #define PG8_WAIT_L(n) asm volatile("s_waitcnt lgkmcnt(" #n ")" ::: "memory")
; #define PG8_BAR __builtin_amdgcn_s_barrier()
; #define PG8_SCHED __builtin_amdgcn_sched_barrier(0)
; __device__ __forceinline__ void gemm_phase(LAS unsigned char* lds, const Params& p, const bf16_t* gA, const bf16_t* gBt, const int gM, const int gN, const int gK, const int epi, const int perm, bf16_t* const Hp, const int goff, const float coef) {
;     ...
;             PG8_WAIT_V(8); PG8_WAIT_L(0); PG8_BAR; PG8_MMA(1, 0, At, B0); PG8_MMA(1, 1, At, B1); PG8_BAR; PG8_SCHED;
;             PG8_LDB(B0, 1, 0); PG8_LDB(B1, 1, 1); PG8_SCHED; PG8_LDA(At, 1, 0); PG8_STAGE(PG8_SA(0, 1), a2 + hstep, voffA);
;             PG8_WAIT_V(8); PG8_WAIT_L(0); PG8_BAR; PG8_MMA(0, 0, At, B0); PG8_MMA(0, 1, At, B1); PG8_BAR; PG8_SCHED;
	s_setprio 0
	s_waitcnt lgkmcnt(0)
	v_mfma_f32_16x16x32_bf16 v[60:63], v[128:131], v[204:207], v[60:63]
	v_mfma_f32_16x16x32_bf16 v[56:59], v[136:139], v[204:207], v[56:59]
	v_mfma_f32_16x16x32_bf16 v[44:47], v[128:131], v[212:215], v[44:47]
	v_mfma_f32_16x16x32_bf16 v[40:43], v[136:139], v[212:215], v[40:43]
	v_mfma_f32_16x16x32_bf16 v[28:31], v[128:131], v[220:223], v[28:31]
	v_mfma_f32_16x16x32_bf16 v[24:27], v[136:139], v[220:223], v[24:27]
	v_mfma_f32_16x16x32_bf16 v[12:15], v[128:131], v[228:231], v[12:15]
	v_mfma_f32_16x16x32_bf16 v[8:11], v[136:139], v[228:231], v[8:11]
	v_mfma_f32_16x16x32_bf16 v[60:63], v[132:135], v[208:211], v[60:63]
	v_mfma_f32_16x16x32_bf16 v[56:59], v[184:187], v[208:211], v[56:59]
	v_mfma_f32_16x16x32_bf16 v[44:47], v[132:135], v[216:219], v[44:47]
	v_mfma_f32_16x16x32_bf16 v[40:43], v[184:187], v[216:219], v[40:43]
	v_mfma_f32_16x16x32_bf16 v[28:31], v[132:135], v[224:227], v[28:31]
	v_mfma_f32_16x16x32_bf16 v[24:27], v[184:187], v[224:227], v[24:27]
	v_mfma_f32_16x16x32_bf16 v[12:15], v[132:135], v[232:235], v[12:15]
	v_mfma_f32_16x16x32_bf16 v[8:11], v[184:187], v[232:235], v[8:11]
	v_mfma_f32_16x16x32_bf16 v[52:55], v[188:191], v[204:207], v[52:55]
	v_mfma_f32_16x16x32_bf16 v[48:51], v[196:199], v[204:207], v[48:51]
	v_mfma_f32_16x16x32_bf16 v[36:39], v[188:191], v[212:215], v[36:39]
	v_mfma_f32_16x16x32_bf16 v[32:35], v[196:199], v[212:215], v[32:35]
	v_mfma_f32_16x16x32_bf16 v[20:23], v[188:191], v[220:223], v[20:23]
	v_mfma_f32_16x16x32_bf16 v[16:19], v[196:199], v[220:223], v[16:19]
	v_mfma_f32_16x16x32_bf16 v[4:7], v[188:191], v[228:231], v[4:7]
	v_mfma_f32_16x16x32_bf16 v[0:3], v[196:199], v[228:231], v[0:3]
	v_mfma_f32_16x16x32_bf16 v[52:55], v[192:195], v[208:211], v[52:55]
	v_mfma_f32_16x16x32_bf16 v[48:51], v[200:203], v[208:211], v[48:51]
	v_mfma_f32_16x16x32_bf16 v[36:39], v[192:195], v[216:219], v[36:39]
	v_mfma_f32_16x16x32_bf16 v[32:35], v[200:203], v[216:219], v[32:35]
	v_mfma_f32_16x16x32_bf16 v[20:23], v[192:195], v[224:227], v[20:23]
	v_mfma_f32_16x16x32_bf16 v[16:19], v[200:203], v[224:227], v[16:19]
	v_mfma_f32_16x16x32_bf16 v[4:7], v[192:195], v[232:235], v[4:7]
	v_mfma_f32_16x16x32_bf16 v[0:3], v[200:203], v[232:235], v[0:3]
	s_setprio 1
	s_barrier
	s_add_i32 s45, 0, 0x18000
	v_add_u32_e32 v150, s45, v171
	s_add_i32 s50, 0, 0x1c000
	ds_read_b128 v[128:131], v150
	ds_read_b128 v[132:135], v150 offset:1024
	ds_read_b128 v[136:139], v150 offset:2048
	ds_read_b128 v[184:187], v150 offset:3072
	v_add_u32_e32 v150, s50, v171
	ds_read_b128 v[188:191], v150
	ds_read_b128 v[192:195], v150 offset:1024
	ds_read_b128 v[196:199], v150 offset:2048
	ds_read_b128 v[200:203], v150 offset:3072
	s_add_u32 s48, s48, 0x80000
	s_addc_u32 s49, s49, 0
	s_mov_b32 m0, s54
	v_lshl_add_u64 v[242:243], s[48:49], 0, v[142:143]
	ds_read_b128 v[204:207], v182 offset:32768
	ds_read_b128 v[208:211], v182 offset:33792
	ds_read_b128 v[212:215], v182 offset:34816
	ds_read_b128 v[216:219], v182 offset:35840
	ds_read_b128 v[220:223], v182 offset:36864
	ds_read_b128 v[224:227], v182 offset:37888
	ds_read_b128 v[228:231], v182 offset:38912
	ds_read_b128 v[232:235], v182 offset:39936
	global_load_lds_dwordx4 v[242:243], off
	v_lshl_add_u64 v[242:243], s[48:49], 0, v[146:147]
	s_mov_b32 m0, s55
	s_nop 0
	global_load_lds_dwordx4 v[242:243], off
	s_waitcnt vmcnt(8)
	s_waitcnt lgkmcnt(0)
	s_barrier
	s_setprio 0
	s_waitcnt lgkmcnt(0)
	v_mfma_f32_16x16x32_bf16 v[124:127], v[128:131], v[204:207], v[124:127]
	v_mfma_f32_16x16x32_bf16 v[120:123], v[136:139], v[204:207], v[120:123]
	v_mfma_f32_16x16x32_bf16 v[108:111], v[128:131], v[212:215], v[108:111]
	v_mfma_f32_16x16x32_bf16 v[104:107], v[136:139], v[212:215], v[104:107]
	v_mfma_f32_16x16x32_bf16 v[92:95], v[128:131], v[220:223], v[92:95]
	v_mfma_f32_16x16x32_bf16 v[88:91], v[136:139], v[220:223], v[88:91]
	v_mfma_f32_16x16x32_bf16 v[76:79], v[128:131], v[228:231], v[76:79]
	v_mfma_f32_16x16x32_bf16 v[72:75], v[136:139], v[228:231], v[72:75]
	v_mfma_f32_16x16x32_bf16 v[124:127], v[132:135], v[208:211], v[124:127]
	v_mfma_f32_16x16x32_bf16 v[120:123], v[184:187], v[208:211], v[120:123]
	v_mfma_f32_16x16x32_bf16 v[108:111], v[132:135], v[216:219], v[108:111]
	v_mfma_f32_16x16x32_bf16 v[104:107], v[184:187], v[216:219], v[104:107]
	v_mfma_f32_16x16x32_bf16 v[92:95], v[132:135], v[224:227], v[92:95]
	v_mfma_f32_16x16x32_bf16 v[88:91], v[184:187], v[224:227], v[88:91]
	v_mfma_f32_16x16x32_bf16 v[76:79], v[132:135], v[232:235], v[76:79]
	v_mfma_f32_16x16x32_bf16 v[72:75], v[184:187], v[232:235], v[72:75]
	v_mfma_f32_16x16x32_bf16 v[116:119], v[188:191], v[204:207], v[116:119]
	v_mfma_f32_16x16x32_bf16 v[112:115], v[196:199], v[204:207], v[112:115]
	v_mfma_f32_16x16x32_bf16 v[100:103], v[188:191], v[212:215], v[100:103]
	v_mfma_f32_16x16x32_bf16 v[96:99], v[196:199], v[212:215], v[96:99]
	v_mfma_f32_16x16x32_bf16 v[84:87], v[188:191], v[220:223], v[84:87]
	v_mfma_f32_16x16x32_bf16 v[80:83], v[196:199], v[220:223], v[80:83]
	v_mfma_f32_16x16x32_bf16 v[68:71], v[188:191], v[228:231], v[68:71]
	v_mfma_f32_16x16x32_bf16 v[64:67], v[196:199], v[228:231], v[64:67]
	v_mfma_f32_16x16x32_bf16 v[116:119], v[192:195], v[208:211], v[116:119]
	v_mfma_f32_16x16x32_bf16 v[112:115], v[200:203], v[208:211], v[112:115]
	v_mfma_f32_16x16x32_bf16 v[100:103], v[192:195], v[216:219], v[100:103]
	v_mfma_f32_16x16x32_bf16 v[96:99], v[200:203], v[216:219], v[96:99]
	v_mfma_f32_16x16x32_bf16 v[84:87], v[192:195], v[224:227], v[84:87]
	v_mfma_f32_16x16x32_bf16 v[80:83], v[200:203], v[224:227], v[80:83]
	v_mfma_f32_16x16x32_bf16 v[68:71], v[192:195], v[232:235], v[68:71]
	v_mfma_f32_16x16x32_bf16 v[64:67], v[200:203], v[232:235], v[64:67]
	s_setprio 1
	s_barrier
; #define PG8_STAGE(bufoff, gbase, voff) do { _Pragma("unroll") for (int _i = 0; _i < 2; ++_i) \
;         __builtin_amdgcn_global_load_lds((const unsigned*)((const char*)(gbase) + (voff)[_i]), (LAS unsigned*)(lds + (bufoff) + ldsw + _i * 8192), 16, 0, 0); } while (0)
; #define PG8_LDA(dst, b, h) do { _Pragma("unroll") for (int m = 0; m < 4; ++m) _Pragma("unroll") for (int k = 0; k < 2; ++k) dst[m][k] = *(const LAS bf16x8*)(lds + PG8_SA(b, h) + aoff + m * 2048 + k * 1024); } while (0)
; #define PG8_MMA(ai, bj, At, Bt) do { __builtin_amdgcn_s_setprio(1); _Pragma("unroll") for (int m = 0; m < 4; ++m) _Pragma("unroll") for (int n = 0; n < 2; ++n) _Pragma("unroll") for (int k = 0; k < 2; ++k) \
;         acc[ai][bj][m][n] = __builtin_amdgcn_mfma_f32_16x16x32_bf16(Bt[n][k], At[m][k], acc[ai][bj][m][n], 0, 0, 0); __builtin_amdgcn_s_setprio(0); } while (0)
; #define PG8_WAIT_V(n) asm volatile("s_waitcnt vmcnt(" #n ")" ::: "memory")
; #define PG8_WAIT_L(n) asm volatile("s_waitcnt lgkmcnt(" #n ")" ::: "memory")
; #define PG8_BAR __builtin_amdgcn_s_barrier()
; #define PG8_SCHED __builtin_amdgcn_sched_barrier(0)
; __device__ __forceinline__ void gemm_epilogue(const Params& p, const int epi, bf16_t* const Hp, const int goff, const float coef, const f32x4 (&acc)[2][2][4][2], const pg8::Unit& u, int wr, int wc, int fr, int fq) {
;     ...
;         const int seg = u.pn >> 2;
;         const bool lat = u.pm < 128;
;         if (seg < 5) {
; __device__ __forceinline__ void gemm_phase(LAS unsigned char* lds, const Params& p, const bf16_t* gA, const bf16_t* gBt, const int gM, const int gN, const int gK, const int epi, const int perm, bf16_t* const Hp, const int goff, const float coef) {
;     ...
;             PG8_LDA(At, 1, 1); PG8_STAGE(PG8_SB(1, 0), b3, voffB); PG8_STAGE(PG8_SB(1, 1), b3 + hstep, voffB); PG8_STAGE(PG8_SA(1, 0), a3, voffA);
;             PG8_WAIT_V(8); PG8_WAIT_L(0); PG8_BAR; PG8_MMA(1, 0, At, B0); PG8_MMA(1, 1, At, B1); PG8_BAR; PG8_SCHED;
;         }
;         if (wr == 0) PG8_BAR;
	s_add_i32 s45, s45, s52
	v_lshl_add_u64 v[168:169], v[168:169], 0, s[10:11]
	s_mov_b32 m0, s45
	ds_read_b128 v[204:207], v182 offset:49152
	ds_read_b128 v[208:211], v182 offset:50176
	ds_read_b128 v[212:215], v182 offset:51200
	ds_read_b128 v[216:219], v182 offset:52224
	ds_read_b128 v[220:223], v182 offset:53248
	ds_read_b128 v[224:227], v182 offset:54272
	ds_read_b128 v[228:231], v182 offset:55296
	ds_read_b128 v[232:235], v182 offset:56320
	global_load_lds_dwordx4 v[168:169], off
	s_add_i32 m0, s45, 0x2000
	s_add_u32 s4, s4, 0x80080
	v_lshl_add_u64 v[168:169], v[236:237], 0, s[10:11]
	s_addc_u32 s5, s5, 0
	s_add_i32 s45, s50, s52
	global_load_lds_dwordx4 v[168:169], off
	v_lshl_add_u64 v[168:169], s[4:5], 0, v[144:145]
	s_mov_b32 m0, s45
	s_nop 0
	global_load_lds_dwordx4 v[168:169], off
	v_lshl_add_u64 v[168:169], s[4:5], 0, v[148:149]
	s_add_i32 m0, s45, 0x2000
	s_nop 0
	global_load_lds_dwordx4 v[168:169], off
	v_lshl_add_u64 v[168:169], v[238:239], 0, s[10:11]
	s_mov_b32 m0, s57
	s_nop 0
	global_load_lds_dwordx4 v[168:169], off
	v_lshl_add_u64 v[168:169], v[240:241], 0, s[10:11]
	s_mov_b32 m0, s58
	s_nop 0
	global_load_lds_dwordx4 v[168:169], off
	s_waitcnt vmcnt(8)
	s_waitcnt lgkmcnt(0)
	s_barrier
	s_setprio 0
	s_waitcnt lgkmcnt(0)
	v_mfma_f32_16x16x32_bf16 v[60:63], v[128:131], v[204:207], v[60:63]
	v_mfma_f32_16x16x32_bf16 v[56:59], v[136:139], v[204:207], v[56:59]
	v_mfma_f32_16x16x32_bf16 v[44:47], v[128:131], v[212:215], v[44:47]
	v_mfma_f32_16x16x32_bf16 v[40:43], v[136:139], v[212:215], v[40:43]
	v_mfma_f32_16x16x32_bf16 v[28:31], v[128:131], v[220:223], v[28:31]
	v_mfma_f32_16x16x32_bf16 v[24:27], v[136:139], v[220:223], v[24:27]
	v_mfma_f32_16x16x32_bf16 v[12:15], v[128:131], v[228:231], v[12:15]
	v_mfma_f32_16x16x32_bf16 v[8:11], v[136:139], v[228:231], v[8:11]
	v_mfma_f32_16x16x32_bf16 v[60:63], v[132:135], v[208:211], v[60:63]
	v_mfma_f32_16x16x32_bf16 v[56:59], v[184:187], v[208:211], v[56:59]
	v_mfma_f32_16x16x32_bf16 v[44:47], v[132:135], v[216:219], v[44:47]
	v_mfma_f32_16x16x32_bf16 v[40:43], v[184:187], v[216:219], v[40:43]
	v_mfma_f32_16x16x32_bf16 v[28:31], v[132:135], v[224:227], v[28:31]
	v_mfma_f32_16x16x32_bf16 v[24:27], v[184:187], v[224:227], v[24:27]
	v_mfma_f32_16x16x32_bf16 v[12:15], v[132:135], v[232:235], v[12:15]
	v_mfma_f32_16x16x32_bf16 v[8:11], v[184:187], v[232:235], v[8:11]
	v_mfma_f32_16x16x32_bf16 v[52:55], v[188:191], v[204:207], v[52:55]
	v_mfma_f32_16x16x32_bf16 v[48:51], v[196:199], v[204:207], v[48:51]
	v_mfma_f32_16x16x32_bf16 v[36:39], v[188:191], v[212:215], v[36:39]
	v_mfma_f32_16x16x32_bf16 v[32:35], v[196:199], v[212:215], v[32:35]
	v_mfma_f32_16x16x32_bf16 v[20:23], v[188:191], v[220:223], v[20:23]
	v_mfma_f32_16x16x32_bf16 v[16:19], v[196:199], v[220:223], v[16:19]
	v_mfma_f32_16x16x32_bf16 v[4:7], v[188:191], v[228:231], v[4:7]
	v_mfma_f32_16x16x32_bf16 v[0:3], v[196:199], v[228:231], v[0:3]
	v_mfma_f32_16x16x32_bf16 v[52:55], v[192:195], v[208:211], v[52:55]
	v_mfma_f32_16x16x32_bf16 v[48:51], v[200:203], v[208:211], v[48:51]
	v_mfma_f32_16x16x32_bf16 v[36:39], v[192:195], v[216:219], v[36:39]
	v_mfma_f32_16x16x32_bf16 v[32:35], v[200:203], v[216:219], v[32:35]
	v_mfma_f32_16x16x32_bf16 v[20:23], v[192:195], v[224:227], v[20:23]
	v_mfma_f32_16x16x32_bf16 v[16:19], v[200:203], v[224:227], v[16:19]
	v_mfma_f32_16x16x32_bf16 v[4:7], v[192:195], v[232:235], v[4:7]
	v_mfma_f32_16x16x32_bf16 v[0:3], v[200:203], v[232:235], v[0:3]
	s_setprio 1
	s_barrier
	s_add_u32 s0, s0, 0x100
	s_addc_u32 s1, s1, 0
	s_add_u32 s33, s33, 0x100
	s_addc_u32 s35, s35, 0
	s_cmp_ge_u32 s37, s22
	s_mov_b32 s45, s37
	s_cbranch_scc0 .LBB0_436
	s_and_b64 vcc, exec, s[12:13]
	s_cbranch_vccnz .LBB0_440
	s_ashr_i32 s14, s46, 2
	s_cmp_gt_i32 s14, 4
	s_mov_b64 s[0:1], -1
	s_cbranch_scc1 .LBB0_441

; #define PG8_STAGE(bufoff, gbase, voff) do { _Pragma("unroll") for (int _i = 0; _i < 2; ++_i) \
;         __builtin_amdgcn_global_load_lds((const unsigned*)((const char*)(gbase) + (voff)[_i]), (LAS unsigned*)(lds + (bufoff) + ldsw + _i * 8192), 16, 0, 0); } while (0)
; #define PG8_LDA(dst, b, h) do { _Pragma("unroll") for (int m = 0; m < 4; ++m) _Pragma("unroll") for (int k = 0; k < 2; ++k) dst[m][k] = *(const LAS bf16x8*)(lds + PG8_SA(b, h) + aoff + m * 2048 + k * 1024); } while (0)
; #define PG8_LDB(dst, b, h) do { _Pragma("unroll") for (int n = 0; n < 2; ++n) _Pragma("unroll") for (int k = 0; k < 2; ++k) dst[n][k] = *(const LAS bf16x8*)(lds + PG8_SB(b, h) + boff + n * 2048 + k * 1024); } while (0)
; #define PG8_MMA(ai, bj, At, Bt) do { __builtin_amdgcn_s_setprio(1); _Pragma("unroll") for (int m = 0; m < 4; ++m) _Pragma("unroll") for (int n = 0; n < 2; ++n) _Pragma("unroll") for (int k = 0; k < 2; ++k) \
;         acc[ai][bj][m][n] = __builtin_amdgcn_mfma_f32_16x16x32_bf16(Bt[n][k], At[m][k], acc[ai][bj][m][n], 0, 0, 0); __builtin_amdgcn_s_setprio(0); } while (0)
; #define PG8_WAIT_V(n) asm volatile("s_waitcnt vmcnt(" #n ")" ::: "memory")
; #define PG8_WAIT_L(n) asm volatile("s_waitcnt lgkmcnt(" #n ")" ::: "memory")
; __device__ __forceinline__ void gemm_phase(LAS unsigned char* lds, const Params& p, const bf16_t* gA, const bf16_t* gBt, const int gM, const int gN, const int gK, const int epi, const int perm, bf16_t* const Hp, const int goff, const float coef) {
;     ...
;         for (int t = 0; t < nt; t += 2) {
;             const bool last = (t == nt - 2);
;             const char* a1 = cA + (size_t)(t + 1) * kstep;
;             const char* a2 = last ? nA : cA + (size_t)(t + 2) * kstep; const char* b2 = last ? nB : cB + (size_t)(t + 2) * kstep;
;             const char* a3 = a2 + kstep; const char* b3 = b2 + kstep;
;             PG8_LDB(B0, 0, 0); PG8_LDB(B1, 0, 1); PG8_SCHED; PG8_LDA(At, 0, 0); PG8_STAGE(PG8_SA(1, 1), a1 + hstep, voffA);
;             PG8_WAIT_V(8); PG8_WAIT_L(0); PG8_BAR; PG8_MMA(0, 0, At, B0); PG8_MMA(0, 1, At, B1); PG8_BAR; PG8_SCHED;
;             PG8_LDA(At, 0, 1); PG8_STAGE(PG8_SB(0, 0), b2, voffB); PG8_STAGE(PG8_SB(0, 1), b2 + hstep, voffB); PG8_STAGE(PG8_SA(0, 0), a2, voffA);
;             PG8_WAIT_V(8); PG8_WAIT_L(0); PG8_BAR; PG8_MMA(1, 0, At, B0); PG8_MMA(1, 1, At, B1); PG8_BAR; PG8_SCHED;
.LBB0_1593:
	ds_read_b128 v[128:131], v174
	ds_read_b128 v[132:135], v174 offset:1024
	ds_read_b128 v[152:155], v174 offset:2048
	ds_read_b128 v[156:159], v174 offset:3072
	ds_read_b128 v[160:163], v175
	ds_read_b128 v[178:181], v175 offset:1024
	ds_read_b128 v[182:185], v175 offset:2048
	ds_read_b128 v[186:189], v175 offset:3072
	s_add_i32 s56, s30, 2
	s_add_u32 s28, s26, 0xfff80080
	s_addc_u32 s29, s27, -1
	s_cmp_eq_u32 s53, s30
	s_cselect_b32 s30, s19, s28
	s_cselect_b32 s31, s13, s29
	s_cselect_b32 s29, s15, s55
	s_cselect_b32 s28, s25, s54
	v_lshl_add_u64 v[222:223], s[26:27], 0, v[146:147]
	s_add_i32 m0, s37, 0xc000
	ds_read_b128 v[190:193], v176
	ds_read_b128 v[194:197], v176 offset:1024
	ds_read_b128 v[198:201], v176 offset:2048
	ds_read_b128 v[202:205], v176 offset:3072
	ds_read_b128 v[206:209], v176 offset:4096
	ds_read_b128 v[210:213], v176 offset:5120
	ds_read_b128 v[214:217], v176 offset:6144
	ds_read_b128 v[218:221], v176 offset:7168
	global_load_lds_dwordx4 v[222:223], off
	v_lshl_add_u64 v[222:223], s[26:27], 0, v[148:149]
	s_add_i32 m0, s37, 0xe000
	s_nop 0
	global_load_lds_dwordx4 v[222:223], off
	s_waitcnt vmcnt(8)
	s_waitcnt lgkmcnt(0)
	s_barrier
	s_setprio 0
	s_waitcnt lgkmcnt(0)
	v_mfma_f32_16x16x32_bf16 v[124:127], v[128:131], v[190:193], v[124:127]
	v_mfma_f32_16x16x32_bf16 v[120:123], v[152:155], v[190:193], v[120:123]
	v_mfma_f32_16x16x32_bf16 v[116:119], v[128:131], v[198:201], v[116:119]
	v_mfma_f32_16x16x32_bf16 v[112:115], v[152:155], v[198:201], v[112:115]
	v_mfma_f32_16x16x32_bf16 v[108:111], v[128:131], v[206:209], v[108:111]
	v_mfma_f32_16x16x32_bf16 v[104:107], v[152:155], v[206:209], v[104:107]
	v_mfma_f32_16x16x32_bf16 v[100:103], v[128:131], v[214:217], v[100:103]
	v_mfma_f32_16x16x32_bf16 v[96:99], v[152:155], v[214:217], v[96:99]
	v_mfma_f32_16x16x32_bf16 v[124:127], v[132:135], v[194:197], v[124:127]
	v_mfma_f32_16x16x32_bf16 v[120:123], v[156:159], v[194:197], v[120:123]
	v_mfma_f32_16x16x32_bf16 v[116:119], v[132:135], v[202:205], v[116:119]
	v_mfma_f32_16x16x32_bf16 v[112:115], v[156:159], v[202:205], v[112:115]
	v_mfma_f32_16x16x32_bf16 v[108:111], v[132:135], v[210:213], v[108:111]
	v_mfma_f32_16x16x32_bf16 v[104:107], v[156:159], v[210:213], v[104:107]
	v_mfma_f32_16x16x32_bf16 v[100:103], v[132:135], v[218:221], v[100:103]
	v_mfma_f32_16x16x32_bf16 v[96:99], v[156:159], v[218:221], v[96:99]
	v_mfma_f32_16x16x32_bf16 v[68:71], v[160:163], v[190:193], v[68:71]
	v_mfma_f32_16x16x32_bf16 v[64:67], v[182:185], v[190:193], v[64:67]
	v_mfma_f32_16x16x32_bf16 v[52:55], v[160:163], v[198:201], v[52:55]
	v_mfma_f32_16x16x32_bf16 v[48:51], v[182:185], v[198:201], v[48:51]
	v_mfma_f32_16x16x32_bf16 v[44:47], v[160:163], v[206:209], v[44:47]
	v_mfma_f32_16x16x32_bf16 v[40:43], v[182:185], v[206:209], v[40:43]
	v_mfma_f32_16x16x32_bf16 v[36:39], v[160:163], v[214:217], v[36:39]
	v_mfma_f32_16x16x32_bf16 v[32:35], v[182:185], v[214:217], v[32:35]
	v_mfma_f32_16x16x32_bf16 v[68:71], v[178:181], v[194:197], v[68:71]
	v_mfma_f32_16x16x32_bf16 v[64:67], v[186:189], v[194:197], v[64:67]
	v_mfma_f32_16x16x32_bf16 v[52:55], v[178:181], v[202:205], v[52:55]
	v_mfma_f32_16x16x32_bf16 v[48:51], v[186:189], v[202:205], v[48:51]
	v_mfma_f32_16x16x32_bf16 v[44:47], v[178:181], v[210:213], v[44:47]
	v_mfma_f32_16x16x32_bf16 v[40:43], v[186:189], v[210:213], v[40:43]
	v_mfma_f32_16x16x32_bf16 v[36:39], v[178:181], v[218:221], v[36:39]
	v_mfma_f32_16x16x32_bf16 v[32:35], v[186:189], v[218:221], v[32:35]
	s_setprio 1
	s_barrier
	s_add_i32 s57, s48, s36
	v_lshl_add_u64 v[222:223], s[28:29], 0, v[138:139]
	s_mov_b32 m0, s57
	ds_read_b128 v[190:193], v176 offset:16384
	ds_read_b128 v[194:197], v176 offset:17408
	ds_read_b128 v[198:201], v176 offset:18432
	ds_read_b128 v[202:205], v176 offset:19456
	ds_read_b128 v[206:209], v176 offset:20480
	ds_read_b128 v[210:213], v176 offset:21504
	ds_read_b128 v[214:217], v176 offset:22528
	ds_read_b128 v[218:221], v176 offset:23552
	global_load_lds_dwordx4 v[222:223], off
	s_add_i32 m0, s57, 0x2000
	s_add_u32 s58, s28, 0x80000
	v_lshl_add_u64 v[224:225], s[28:29], 0, v[144:145]
	s_addc_u32 s59, s29, 0
	s_add_i32 s57, s49, s36
	global_load_lds_dwordx4 v[224:225], off
	v_lshl_add_u64 v[226:227], s[58:59], 0, v[138:139]
	s_mov_b32 m0, s57
	v_lshl_add_u64 v[228:229], s[30:31], 0, v[142:143]
	global_load_lds_dwordx4 v[226:227], off
	v_lshl_add_u64 v[226:227], s[58:59], 0, v[144:145]
	s_add_i32 m0, s57, 0x2000
	s_nop 0
	global_load_lds_dwordx4 v[226:227], off
	v_lshl_add_u64 v[226:227], s[30:31], 0, v[136:137]
	s_mov_b32 m0, s37
	s_nop 0
	global_load_lds_dwordx4 v[226:227], off
	s_mov_b32 m0, s38
	s_nop 0
	global_load_lds_dwordx4 v[228:229], off
	s_waitcnt vmcnt(8)
	s_waitcnt lgkmcnt(0)
	s_barrier
; #define PG8_STAGE(bufoff, gbase, voff) do { _Pragma("unroll") for (int _i = 0; _i < 2; ++_i) \
;         __builtin_amdgcn_global_load_lds((const unsigned*)((const char*)(gbase) + (voff)[_i]), (LAS unsigned*)(lds + (bufoff) + ldsw + _i * 8192), 16, 0, 0); } while (0)
; #define PG8_LDA(dst, b, h) do { _Pragma("unroll") for (int m = 0; m < 4; ++m) _Pragma("unroll") for (int k = 0; k < 2; ++k) dst[m][k] = *(const LAS bf16x8*)(lds + PG8_SA(b, h) + aoff + m * 2048 + k * 1024); } while (0)
; #define PG8_LDB(dst, b, h) do { _Pragma("unroll") for (int n = 0; n < 2; ++n) _Pragma("unroll") for (int k = 0; k < 2; ++k) dst[n][k] = *(const LAS bf16x8*)(lds + PG8_SB(b, h) + boff + n * 2048 + k * 1024); } while (0)
; #define PG8_MMA(ai, bj, At, Bt) do { __builtin_amdgcn_s_setprio(1); _Pragma("unroll") for (int m = 0; m < 4; ++m) _Pragma("unroll") for (int n = 0; n < 2; ++n) _Pragma("unroll") for (int k = 0; k < 2; ++k) \
;         acc[ai][bj][m][n] = __builtin_amdgcn_mfma_f32_16x16x32_bf16(Bt[n][k], At[m][k], acc[ai][bj][m][n], 0, 0, 0); __builtin_amdgcn_s_setprio(0); } while (0)
; #define PG8_WAIT_V(n) asm volatile("s_waitcnt vmcnt(" #n ")" ::: "memory")
; #define PG8_WAIT_L(n) asm volatile("s_waitcnt lgkmcnt(" #n ")" ::: "memory")
; #define PG8_BAR __builtin_amdgcn_s_barrier()
; #define PG8_SCHED __builtin_amdgcn_sched_barrier(0)
; __device__ __forceinline__ void gemm_phase(LAS unsigned char* lds, const Params& p, const bf16_t* gA, const bf16_t* gBt, const int gM, const int gN, const int gK, const int epi, const int perm, bf16_t* const Hp, const int goff, const float coef) {
;     ...
;             PG8_WAIT_V(8); PG8_WAIT_L(0); PG8_BAR; PG8_MMA(1, 0, At, B0); PG8_MMA(1, 1, At, B1); PG8_BAR; PG8_SCHED;
;             PG8_LDB(B0, 1, 0); PG8_LDB(B1, 1, 1); PG8_SCHED; PG8_LDA(At, 1, 0); PG8_STAGE(PG8_SA(0, 1), a2 + hstep, voffA);
;             PG8_WAIT_V(8); PG8_WAIT_L(0); PG8_BAR; PG8_MMA(0, 0, At, B0); PG8_MMA(0, 1, At, B1); PG8_BAR; PG8_SCHED;
	s_setprio 0
	s_waitcnt lgkmcnt(0)
	v_mfma_f32_16x16x32_bf16 v[92:95], v[128:131], v[190:193], v[92:95]
	v_mfma_f32_16x16x32_bf16 v[88:91], v[152:155], v[190:193], v[88:91]
	v_mfma_f32_16x16x32_bf16 v[84:87], v[128:131], v[198:201], v[84:87]
	v_mfma_f32_16x16x32_bf16 v[80:83], v[152:155], v[198:201], v[80:83]
	v_mfma_f32_16x16x32_bf16 v[76:79], v[128:131], v[206:209], v[76:79]
	v_mfma_f32_16x16x32_bf16 v[72:75], v[152:155], v[206:209], v[72:75]
	v_mfma_f32_16x16x32_bf16 v[60:63], v[128:131], v[214:217], v[60:63]
	v_mfma_f32_16x16x32_bf16 v[56:59], v[152:155], v[214:217], v[56:59]
	v_mfma_f32_16x16x32_bf16 v[92:95], v[132:135], v[194:197], v[92:95]
	v_mfma_f32_16x16x32_bf16 v[88:91], v[156:159], v[194:197], v[88:91]
	v_mfma_f32_16x16x32_bf16 v[84:87], v[132:135], v[202:205], v[84:87]
	v_mfma_f32_16x16x32_bf16 v[80:83], v[156:159], v[202:205], v[80:83]
	v_mfma_f32_16x16x32_bf16 v[76:79], v[132:135], v[210:213], v[76:79]
	v_mfma_f32_16x16x32_bf16 v[72:75], v[156:159], v[210:213], v[72:75]
	v_mfma_f32_16x16x32_bf16 v[60:63], v[132:135], v[218:221], v[60:63]
	v_mfma_f32_16x16x32_bf16 v[56:59], v[156:159], v[218:221], v[56:59]
	v_mfma_f32_16x16x32_bf16 v[28:31], v[160:163], v[190:193], v[28:31]
	v_mfma_f32_16x16x32_bf16 v[24:27], v[182:185], v[190:193], v[24:27]
	v_mfma_f32_16x16x32_bf16 v[20:23], v[160:163], v[198:201], v[20:23]
	v_mfma_f32_16x16x32_bf16 v[16:19], v[182:185], v[198:201], v[16:19]
	v_mfma_f32_16x16x32_bf16 v[12:15], v[160:163], v[206:209], v[12:15]
	v_mfma_f32_16x16x32_bf16 v[8:11], v[182:185], v[206:209], v[8:11]
	v_mfma_f32_16x16x32_bf16 v[4:7], v[160:163], v[214:217], v[4:7]
	v_mfma_f32_16x16x32_bf16 v[0:3], v[182:185], v[214:217], v[0:3]
	v_mfma_f32_16x16x32_bf16 v[28:31], v[178:181], v[194:197], v[28:31]
	v_mfma_f32_16x16x32_bf16 v[24:27], v[186:189], v[194:197], v[24:27]
	v_mfma_f32_16x16x32_bf16 v[20:23], v[178:181], v[202:205], v[20:23]
	v_mfma_f32_16x16x32_bf16 v[16:19], v[186:189], v[202:205], v[16:19]
	v_mfma_f32_16x16x32_bf16 v[12:15], v[178:181], v[210:213], v[12:15]
	v_mfma_f32_16x16x32_bf16 v[8:11], v[186:189], v[210:213], v[8:11]
	v_mfma_f32_16x16x32_bf16 v[4:7], v[178:181], v[218:221], v[4:7]
	v_mfma_f32_16x16x32_bf16 v[0:3], v[186:189], v[218:221], v[0:3]
	s_setprio 1
	s_barrier
	s_add_i32 s57, 0, 0x18000
	v_add_u32_e32 v141, s57, v165
	s_add_i32 s58, 0, 0x1c000
	ds_read_b128 v[128:131], v141
	ds_read_b128 v[132:135], v141 offset:1024
	ds_read_b128 v[152:155], v141 offset:2048
	ds_read_b128 v[156:159], v141 offset:3072
	v_add_u32_e32 v141, s58, v165
	ds_read_b128 v[160:163], v141
	ds_read_b128 v[178:181], v141 offset:1024
	ds_read_b128 v[182:185], v141 offset:2048
	ds_read_b128 v[186:189], v141 offset:3072
	s_add_u32 s30, s30, 0x80000
	s_addc_u32 s31, s31, 0
	s_mov_b32 m0, s39
	v_lshl_add_u64 v[230:231], s[30:31], 0, v[136:137]
	ds_read_b128 v[190:193], v176 offset:32768
	ds_read_b128 v[194:197], v176 offset:33792
	ds_read_b128 v[198:201], v176 offset:34816
	ds_read_b128 v[202:205], v176 offset:35840
	ds_read_b128 v[206:209], v176 offset:36864
	ds_read_b128 v[210:213], v176 offset:37888
	ds_read_b128 v[214:217], v176 offset:38912
	ds_read_b128 v[218:221], v176 offset:39936
	global_load_lds_dwordx4 v[230:231], off
	v_lshl_add_u64 v[230:231], s[30:31], 0, v[142:143]
	s_mov_b32 m0, s40
	s_nop 0
	global_load_lds_dwordx4 v[230:231], off
	s_waitcnt vmcnt(8)
	s_waitcnt lgkmcnt(0)
	s_barrier
	s_setprio 0
	s_waitcnt lgkmcnt(0)
	v_mfma_f32_16x16x32_bf16 v[124:127], v[128:131], v[190:193], v[124:127]
	v_mfma_f32_16x16x32_bf16 v[120:123], v[152:155], v[190:193], v[120:123]
	v_mfma_f32_16x16x32_bf16 v[116:119], v[128:131], v[198:201], v[116:119]
	v_mfma_f32_16x16x32_bf16 v[112:115], v[152:155], v[198:201], v[112:115]
	v_mfma_f32_16x16x32_bf16 v[108:111], v[128:131], v[206:209], v[108:111]
	v_mfma_f32_16x16x32_bf16 v[104:107], v[152:155], v[206:209], v[104:107]
	v_mfma_f32_16x16x32_bf16 v[100:103], v[128:131], v[214:217], v[100:103]
	v_mfma_f32_16x16x32_bf16 v[96:99], v[152:155], v[214:217], v[96:99]
	v_mfma_f32_16x16x32_bf16 v[124:127], v[132:135], v[194:197], v[124:127]
	v_mfma_f32_16x16x32_bf16 v[120:123], v[156:159], v[194:197], v[120:123]
	v_mfma_f32_16x16x32_bf16 v[116:119], v[132:135], v[202:205], v[116:119]
	v_mfma_f32_16x16x32_bf16 v[112:115], v[156:159], v[202:205], v[112:115]
	v_mfma_f32_16x16x32_bf16 v[108:111], v[132:135], v[210:213], v[108:111]
	v_mfma_f32_16x16x32_bf16 v[104:107], v[156:159], v[210:213], v[104:107]
	v_mfma_f32_16x16x32_bf16 v[100:103], v[132:135], v[218:221], v[100:103]
	v_mfma_f32_16x16x32_bf16 v[96:99], v[156:159], v[218:221], v[96:99]
	v_mfma_f32_16x16x32_bf16 v[68:71], v[160:163], v[190:193], v[68:71]
	v_mfma_f32_16x16x32_bf16 v[64:67], v[182:185], v[190:193], v[64:67]
	v_mfma_f32_16x16x32_bf16 v[52:55], v[160:163], v[198:201], v[52:55]
	v_mfma_f32_16x16x32_bf16 v[48:51], v[182:185], v[198:201], v[48:51]
	v_mfma_f32_16x16x32_bf16 v[44:47], v[160:163], v[206:209], v[44:47]
	v_mfma_f32_16x16x32_bf16 v[40:43], v[182:185], v[206:209], v[40:43]
	v_mfma_f32_16x16x32_bf16 v[36:39], v[160:163], v[214:217], v[36:39]
	v_mfma_f32_16x16x32_bf16 v[32:35], v[182:185], v[214:217], v[32:35]
	v_mfma_f32_16x16x32_bf16 v[68:71], v[178:181], v[194:197], v[68:71]
	v_mfma_f32_16x16x32_bf16 v[64:67], v[186:189], v[194:197], v[64:67]
	v_mfma_f32_16x16x32_bf16 v[52:55], v[178:181], v[202:205], v[52:55]
	v_mfma_f32_16x16x32_bf16 v[48:51], v[186:189], v[202:205], v[48:51]
	v_mfma_f32_16x16x32_bf16 v[44:47], v[178:181], v[210:213], v[44:47]
	v_mfma_f32_16x16x32_bf16 v[40:43], v[186:189], v[210:213], v[40:43]
	v_mfma_f32_16x16x32_bf16 v[36:39], v[178:181], v[218:221], v[36:39]
	v_mfma_f32_16x16x32_bf16 v[32:35], v[186:189], v[218:221], v[32:35]
	s_setprio 1
	s_barrier
; #define PG8_STAGE(bufoff, gbase, voff) do { _Pragma("unroll") for (int _i = 0; _i < 2; ++_i) \
;         __builtin_amdgcn_global_load_lds((const unsigned*)((const char*)(gbase) + (voff)[_i]), (LAS unsigned*)(lds + (bufoff) + ldsw + _i * 8192), 16, 0, 0); } while (0)
; #define PG8_LDA(dst, b, h) do { _Pragma("unroll") for (int m = 0; m < 4; ++m) _Pragma("unroll") for (int k = 0; k < 2; ++k) dst[m][k] = *(const LAS bf16x8*)(lds + PG8_SA(b, h) + aoff + m * 2048 + k * 1024); } while (0)
; #define PG8_MMA(ai, bj, At, Bt) do { __builtin_amdgcn_s_setprio(1); _Pragma("unroll") for (int m = 0; m < 4; ++m) _Pragma("unroll") for (int n = 0; n < 2; ++n) _Pragma("unroll") for (int k = 0; k < 2; ++k) \
;         acc[ai][bj][m][n] = __builtin_amdgcn_mfma_f32_16x16x32_bf16(Bt[n][k], At[m][k], acc[ai][bj][m][n], 0, 0, 0); __builtin_amdgcn_s_setprio(0); } while (0)
; #define PG8_WAIT_V(n) asm volatile("s_waitcnt vmcnt(" #n ")" ::: "memory")
; #define PG8_WAIT_L(n) asm volatile("s_waitcnt lgkmcnt(" #n ")" ::: "memory")
; #define PG8_BAR __builtin_amdgcn_s_barrier()
; #define PG8_SCHED __builtin_amdgcn_sched_barrier(0)
; __device__ __forceinline__ void gemm_phase(LAS unsigned char* lds, const Params& p, const bf16_t* gA, const bf16_t* gBt, const int gM, const int gN, const int gK, const int epi, const int perm, bf16_t* const Hp, const int goff, const float coef) {
;     ...
;             PG8_LDA(At, 1, 1); PG8_STAGE(PG8_SB(1, 0), b3, voffB); PG8_STAGE(PG8_SB(1, 1), b3 + hstep, voffB); PG8_STAGE(PG8_SA(1, 0), a3, voffA);
;             PG8_WAIT_V(8); PG8_WAIT_L(0); PG8_BAR; PG8_MMA(1, 0, At, B0); PG8_MMA(1, 1, At, B1); PG8_BAR; PG8_SCHED;
;         }
;         if (wr == 0) PG8_BAR;
	s_add_i32 s30, s57, s36
	v_lshl_add_u64 v[222:223], v[222:223], 0, s[8:9]
	s_mov_b32 m0, s30
	ds_read_b128 v[190:193], v176 offset:49152
	ds_read_b128 v[194:197], v176 offset:50176
	ds_read_b128 v[198:201], v176 offset:51200
	ds_read_b128 v[202:205], v176 offset:52224
	ds_read_b128 v[206:209], v176 offset:53248
	ds_read_b128 v[210:213], v176 offset:54272
	ds_read_b128 v[214:217], v176 offset:55296
	ds_read_b128 v[218:221], v176 offset:56320
	global_load_lds_dwordx4 v[222:223], off
	s_add_i32 m0, s30, 0x2000
	s_add_u32 s28, s28, 0x80080
	v_lshl_add_u64 v[222:223], v[224:225], 0, s[8:9]
	s_addc_u32 s29, s29, 0
	s_add_i32 s30, s58, s36
	global_load_lds_dwordx4 v[222:223], off
	v_lshl_add_u64 v[222:223], s[28:29], 0, v[138:139]
	s_mov_b32 m0, s30
	s_nop 0
	global_load_lds_dwordx4 v[222:223], off
	v_lshl_add_u64 v[222:223], s[28:29], 0, v[144:145]
	s_add_i32 m0, s30, 0x2000
	s_nop 0
	global_load_lds_dwordx4 v[222:223], off
	v_lshl_add_u64 v[222:223], v[226:227], 0, s[8:9]
	s_mov_b32 m0, s44
	s_nop 0
	global_load_lds_dwordx4 v[222:223], off
	v_lshl_add_u64 v[222:223], v[228:229], 0, s[8:9]
	s_mov_b32 m0, s45
	s_nop 0
	global_load_lds_dwordx4 v[222:223], off
	s_waitcnt vmcnt(8)
	s_waitcnt lgkmcnt(0)
	s_barrier
	s_setprio 0
	s_waitcnt lgkmcnt(0)
	v_mfma_f32_16x16x32_bf16 v[92:95], v[128:131], v[190:193], v[92:95]
	v_mfma_f32_16x16x32_bf16 v[88:91], v[152:155], v[190:193], v[88:91]
	v_mfma_f32_16x16x32_bf16 v[84:87], v[128:131], v[198:201], v[84:87]
	v_mfma_f32_16x16x32_bf16 v[80:83], v[152:155], v[198:201], v[80:83]
	v_mfma_f32_16x16x32_bf16 v[76:79], v[128:131], v[206:209], v[76:79]
	v_mfma_f32_16x16x32_bf16 v[72:75], v[152:155], v[206:209], v[72:75]
	v_mfma_f32_16x16x32_bf16 v[60:63], v[128:131], v[214:217], v[60:63]
	v_mfma_f32_16x16x32_bf16 v[56:59], v[152:155], v[214:217], v[56:59]
	v_mfma_f32_16x16x32_bf16 v[92:95], v[132:135], v[194:197], v[92:95]
	v_mfma_f32_16x16x32_bf16 v[88:91], v[156:159], v[194:197], v[88:91]
	v_mfma_f32_16x16x32_bf16 v[84:87], v[132:135], v[202:205], v[84:87]
	v_mfma_f32_16x16x32_bf16 v[80:83], v[156:159], v[202:205], v[80:83]
	v_mfma_f32_16x16x32_bf16 v[76:79], v[132:135], v[210:213], v[76:79]
	v_mfma_f32_16x16x32_bf16 v[72:75], v[156:159], v[210:213], v[72:75]
	v_mfma_f32_16x16x32_bf16 v[60:63], v[132:135], v[218:221], v[60:63]
	v_mfma_f32_16x16x32_bf16 v[56:59], v[156:159], v[218:221], v[56:59]
	v_mfma_f32_16x16x32_bf16 v[28:31], v[160:163], v[190:193], v[28:31]
	v_mfma_f32_16x16x32_bf16 v[24:27], v[182:185], v[190:193], v[24:27]
	v_mfma_f32_16x16x32_bf16 v[20:23], v[160:163], v[198:201], v[20:23]
	v_mfma_f32_16x16x32_bf16 v[16:19], v[182:185], v[198:201], v[16:19]
	v_mfma_f32_16x16x32_bf16 v[12:15], v[160:163], v[206:209], v[12:15]
	v_mfma_f32_16x16x32_bf16 v[8:11], v[182:185], v[206:209], v[8:11]
	v_mfma_f32_16x16x32_bf16 v[4:7], v[160:163], v[214:217], v[4:7]
	v_mfma_f32_16x16x32_bf16 v[0:3], v[182:185], v[214:217], v[0:3]
	v_mfma_f32_16x16x32_bf16 v[28:31], v[178:181], v[194:197], v[28:31]
	v_mfma_f32_16x16x32_bf16 v[24:27], v[186:189], v[194:197], v[24:27]
	v_mfma_f32_16x16x32_bf16 v[20:23], v[178:181], v[202:205], v[20:23]
	v_mfma_f32_16x16x32_bf16 v[16:19], v[186:189], v[202:205], v[16:19]
	v_mfma_f32_16x16x32_bf16 v[12:15], v[178:181], v[210:213], v[12:15]
	v_mfma_f32_16x16x32_bf16 v[8:11], v[186:189], v[210:213], v[8:11]
	v_mfma_f32_16x16x32_bf16 v[4:7], v[178:181], v[218:221], v[4:7]
	v_mfma_f32_16x16x32_bf16 v[0:3], v[186:189], v[218:221], v[0:3]
	s_setprio 1
	s_barrier
	s_add_u32 s26, s26, 0x100
	s_addc_u32 s27, s27, 0
	s_add_u32 s54, s54, 0x100
	s_addc_u32 s55, s55, 0
	s_cmp_ge_u32 s56, s52
	s_mov_b32 s30, s56
	s_cbranch_scc0 .LBB0_1593
	s_and_b64 vcc, exec, s[10:11]
	s_cbranch_vccz .LBB0_1596
	s_barrier

; #define PG8_STAGE(bufoff, gbase, voff) do { _Pragma("unroll") for (int _i = 0; _i < 2; ++_i) \
;         __builtin_amdgcn_global_load_lds((const unsigned*)((const char*)(gbase) + (voff)[_i]), (LAS unsigned*)(lds + (bufoff) + ldsw + _i * 8192), 16, 0, 0); } while (0)
; #define PG8_LDA(dst, b, h) do { _Pragma("unroll") for (int m = 0; m < 4; ++m) _Pragma("unroll") for (int k = 0; k < 2; ++k) dst[m][k] = *(const LAS bf16x8*)(lds + PG8_SA(b, h) + aoff + m * 2048 + k * 1024); } while (0)
; #define PG8_LDB(dst, b, h) do { _Pragma("unroll") for (int n = 0; n < 2; ++n) _Pragma("unroll") for (int k = 0; k < 2; ++k) dst[n][k] = *(const LAS bf16x8*)(lds + PG8_SB(b, h) + boff + n * 2048 + k * 1024); } while (0)
; #define PG8_MMA(ai, bj, At, Bt) do { __builtin_amdgcn_s_setprio(1); _Pragma("unroll") for (int m = 0; m < 4; ++m) _Pragma("unroll") for (int n = 0; n < 2; ++n) _Pragma("unroll") for (int k = 0; k < 2; ++k) \
;         acc[ai][bj][m][n] = __builtin_amdgcn_mfma_f32_16x16x32_bf16(Bt[n][k], At[m][k], acc[ai][bj][m][n], 0, 0, 0); __builtin_amdgcn_s_setprio(0); } while (0)
; #define PG8_WAIT_V(n) asm volatile("s_waitcnt vmcnt(" #n ")" ::: "memory")
; #define PG8_WAIT_L(n) asm volatile("s_waitcnt lgkmcnt(" #n ")" ::: "memory")
; __device__ __forceinline__ void gemm_phase(LAS unsigned char* lds, const Params& p, const bf16_t* gA, const bf16_t* gBt, const int gM, const int gN, const int gK, const int epi, const int perm, bf16_t* const Hp, const int goff, const float coef) {
;     ...
;         for (int t = 0; t < nt; t += 2) {
;             const bool last = (t == nt - 2);
;             const char* a1 = cA + (size_t)(t + 1) * kstep;
;             const char* a2 = last ? nA : cA + (size_t)(t + 2) * kstep; const char* b2 = last ? nB : cB + (size_t)(t + 2) * kstep;
;             const char* a3 = a2 + kstep; const char* b3 = b2 + kstep;
;             PG8_LDB(B0, 0, 0); PG8_LDB(B1, 0, 1); PG8_SCHED; PG8_LDA(At, 0, 0); PG8_STAGE(PG8_SA(1, 1), a1 + hstep, voffA);
;             PG8_WAIT_V(8); PG8_WAIT_L(0); PG8_BAR; PG8_MMA(0, 0, At, B0); PG8_MMA(0, 1, At, B1); PG8_BAR; PG8_SCHED;
;             PG8_LDA(At, 0, 1); PG8_STAGE(PG8_SB(0, 0), b2, voffB); PG8_STAGE(PG8_SB(0, 1), b2 + hstep, voffB); PG8_STAGE(PG8_SA(0, 0), a2, voffA);
;             PG8_WAIT_V(8); PG8_WAIT_L(0); PG8_BAR; PG8_MMA(1, 0, At, B0); PG8_MMA(1, 1, At, B1); PG8_BAR; PG8_SCHED;
.LBB0_1737:
	ds_read_b128 v[160:163], v156
	ds_read_b128 v[164:167], v156 offset:1024
	ds_read_b128 v[168:171], v156 offset:2048
	ds_read_b128 v[172:175], v156 offset:3072
	ds_read_b128 v[176:179], v157
	ds_read_b128 v[180:183], v157 offset:1024
	ds_read_b128 v[184:187], v157 offset:2048
	ds_read_b128 v[188:191], v157 offset:3072
	s_add_i32 s54, s30, 2
	s_add_u32 s28, s26, 0xfff80080
	s_addc_u32 s29, s27, -1
	s_cmp_eq_u32 s51, s30
	s_cselect_b32 s30, s48, s28
	s_cselect_b32 s31, s13, s29
	s_cselect_b32 s29, s15, s53
	s_cselect_b32 s28, s49, s52
	v_lshl_add_u64 v[144:145], s[26:27], 0, v[136:137]
	s_add_i32 m0, s23, 0xc000
	ds_read_b128 v[192:195], v158
	ds_read_b128 v[196:199], v158 offset:1024
	ds_read_b128 v[200:203], v158 offset:2048
	ds_read_b128 v[204:207], v158 offset:3072
	ds_read_b128 v[208:211], v158 offset:4096
	ds_read_b128 v[212:215], v158 offset:5120
	ds_read_b128 v[216:219], v158 offset:6144
	ds_read_b128 v[220:223], v158 offset:7168
	global_load_lds_dwordx4 v[144:145], off
	v_lshl_add_u64 v[144:145], s[26:27], 0, v[138:139]
	s_add_i32 m0, s23, 0xe000
	s_nop 0
	global_load_lds_dwordx4 v[144:145], off
	s_waitcnt vmcnt(8)
	s_waitcnt lgkmcnt(0)
	s_barrier
	s_setprio 0
	s_waitcnt lgkmcnt(0)
	v_mfma_f32_16x16x32_bf16 v[124:127], v[160:163], v[192:195], v[124:127]
	v_mfma_f32_16x16x32_bf16 v[120:123], v[168:171], v[192:195], v[120:123]
	v_mfma_f32_16x16x32_bf16 v[108:111], v[160:163], v[200:203], v[108:111]
	v_mfma_f32_16x16x32_bf16 v[104:107], v[168:171], v[200:203], v[104:107]
	v_mfma_f32_16x16x32_bf16 v[92:95], v[160:163], v[208:211], v[92:95]
	v_mfma_f32_16x16x32_bf16 v[88:91], v[168:171], v[208:211], v[88:91]
	v_mfma_f32_16x16x32_bf16 v[76:79], v[160:163], v[216:219], v[76:79]
	v_mfma_f32_16x16x32_bf16 v[72:75], v[168:171], v[216:219], v[72:75]
	v_mfma_f32_16x16x32_bf16 v[124:127], v[164:167], v[196:199], v[124:127]
	v_mfma_f32_16x16x32_bf16 v[120:123], v[172:175], v[196:199], v[120:123]
	v_mfma_f32_16x16x32_bf16 v[108:111], v[164:167], v[204:207], v[108:111]
	v_mfma_f32_16x16x32_bf16 v[104:107], v[172:175], v[204:207], v[104:107]
	v_mfma_f32_16x16x32_bf16 v[92:95], v[164:167], v[212:215], v[92:95]
	v_mfma_f32_16x16x32_bf16 v[88:91], v[172:175], v[212:215], v[88:91]
	v_mfma_f32_16x16x32_bf16 v[76:79], v[164:167], v[220:223], v[76:79]
	v_mfma_f32_16x16x32_bf16 v[72:75], v[172:175], v[220:223], v[72:75]
	v_mfma_f32_16x16x32_bf16 v[116:119], v[176:179], v[192:195], v[116:119]
	v_mfma_f32_16x16x32_bf16 v[112:115], v[184:187], v[192:195], v[112:115]
	v_mfma_f32_16x16x32_bf16 v[100:103], v[176:179], v[200:203], v[100:103]
	v_mfma_f32_16x16x32_bf16 v[96:99], v[184:187], v[200:203], v[96:99]
	v_mfma_f32_16x16x32_bf16 v[84:87], v[176:179], v[208:211], v[84:87]
	v_mfma_f32_16x16x32_bf16 v[80:83], v[184:187], v[208:211], v[80:83]
	v_mfma_f32_16x16x32_bf16 v[68:71], v[176:179], v[216:219], v[68:71]
	v_mfma_f32_16x16x32_bf16 v[64:67], v[184:187], v[216:219], v[64:67]
	v_mfma_f32_16x16x32_bf16 v[116:119], v[180:183], v[196:199], v[116:119]
	v_mfma_f32_16x16x32_bf16 v[112:115], v[188:191], v[196:199], v[112:115]
	v_mfma_f32_16x16x32_bf16 v[100:103], v[180:183], v[204:207], v[100:103]
	v_mfma_f32_16x16x32_bf16 v[96:99], v[188:191], v[204:207], v[96:99]
	v_mfma_f32_16x16x32_bf16 v[84:87], v[180:183], v[212:215], v[84:87]
	v_mfma_f32_16x16x32_bf16 v[80:83], v[188:191], v[212:215], v[80:83]
	v_mfma_f32_16x16x32_bf16 v[68:71], v[180:183], v[220:223], v[68:71]
	v_mfma_f32_16x16x32_bf16 v[64:67], v[188:191], v[220:223], v[64:67]
	s_setprio 1
	s_barrier
	s_add_i32 s55, s44, s36
	v_lshl_add_u64 v[144:145], s[28:29], 0, v[130:131]
	s_mov_b32 m0, s55
	ds_read_b128 v[192:195], v158 offset:16384
	ds_read_b128 v[196:199], v158 offset:17408
	ds_read_b128 v[200:203], v158 offset:18432
	ds_read_b128 v[204:207], v158 offset:19456
	ds_read_b128 v[208:211], v158 offset:20480
	ds_read_b128 v[212:215], v158 offset:21504
	ds_read_b128 v[216:219], v158 offset:22528
	ds_read_b128 v[220:223], v158 offset:23552
	global_load_lds_dwordx4 v[144:145], off
	s_add_i32 m0, s55, 0x2000
	s_add_u32 s56, s28, 0x80000
	v_lshl_add_u64 v[224:225], s[28:29], 0, v[134:135]
	s_addc_u32 s57, s29, 0
	s_add_i32 s55, s45, s36
	global_load_lds_dwordx4 v[224:225], off
	v_lshl_add_u64 v[226:227], s[56:57], 0, v[130:131]
	s_mov_b32 m0, s55
	v_lshl_add_u64 v[228:229], s[30:31], 0, v[132:133]
	global_load_lds_dwordx4 v[226:227], off
	v_lshl_add_u64 v[226:227], s[56:57], 0, v[134:135]
	s_add_i32 m0, s55, 0x2000
	s_nop 0
	global_load_lds_dwordx4 v[226:227], off
	v_lshl_add_u64 v[226:227], s[30:31], 0, v[128:129]
	s_mov_b32 m0, s23
	s_nop 0
	global_load_lds_dwordx4 v[226:227], off
	s_mov_b32 m0, s25
	s_nop 0
	global_load_lds_dwordx4 v[228:229], off
	s_waitcnt vmcnt(8)
	s_waitcnt lgkmcnt(0)
	s_barrier
; #define PG8_STAGE(bufoff, gbase, voff) do { _Pragma("unroll") for (int _i = 0; _i < 2; ++_i) \
;         __builtin_amdgcn_global_load_lds((const unsigned*)((const char*)(gbase) + (voff)[_i]), (LAS unsigned*)(lds + (bufoff) + ldsw + _i * 8192), 16, 0, 0); } while (0)
; #define PG8_LDA(dst, b, h) do { _Pragma("unroll") for (int m = 0; m < 4; ++m) _Pragma("unroll") for (int k = 0; k < 2; ++k) dst[m][k] = *(const LAS bf16x8*)(lds + PG8_SA(b, h) + aoff + m * 2048 + k * 1024); } while (0)
; #define PG8_LDB(dst, b, h) do { _Pragma("unroll") for (int n = 0; n < 2; ++n) _Pragma("unroll") for (int k = 0; k < 2; ++k) dst[n][k] = *(const LAS bf16x8*)(lds + PG8_SB(b, h) + boff + n * 2048 + k * 1024); } while (0)
; #define PG8_MMA(ai, bj, At, Bt) do { __builtin_amdgcn_s_setprio(1); _Pragma("unroll") for (int m = 0; m < 4; ++m) _Pragma("unroll") for (int n = 0; n < 2; ++n) _Pragma("unroll") for (int k = 0; k < 2; ++k) \
;         acc[ai][bj][m][n] = __builtin_amdgcn_mfma_f32_16x16x32_bf16(Bt[n][k], At[m][k], acc[ai][bj][m][n], 0, 0, 0); __builtin_amdgcn_s_setprio(0); } while (0)
; #define PG8_WAIT_V(n) asm volatile("s_waitcnt vmcnt(" #n ")" ::: "memory")
; #define PG8_WAIT_L(n) asm volatile("s_waitcnt lgkmcnt(" #n ")" ::: "memory")
; #define PG8_BAR __builtin_amdgcn_s_barrier()
; #define PG8_SCHED __builtin_amdgcn_sched_barrier(0)
; __device__ __forceinline__ void gemm_phase(LAS unsigned char* lds, const Params& p, const bf16_t* gA, const bf16_t* gBt, const int gM, const int gN, const int gK, const int epi, const int perm, bf16_t* const Hp, const int goff, const float coef) {
;     ...
;             PG8_WAIT_V(8); PG8_WAIT_L(0); PG8_BAR; PG8_MMA(1, 0, At, B0); PG8_MMA(1, 1, At, B1); PG8_BAR; PG8_SCHED;
;             PG8_LDB(B0, 1, 0); PG8_LDB(B1, 1, 1); PG8_SCHED; PG8_LDA(At, 1, 0); PG8_STAGE(PG8_SA(0, 1), a2 + hstep, voffA);
;             PG8_WAIT_V(8); PG8_WAIT_L(0); PG8_BAR; PG8_MMA(0, 0, At, B0); PG8_MMA(0, 1, At, B1); PG8_BAR; PG8_SCHED;
	s_setprio 0
	s_waitcnt lgkmcnt(0)
	v_mfma_f32_16x16x32_bf16 v[60:63], v[160:163], v[192:195], v[60:63]
	v_mfma_f32_16x16x32_bf16 v[56:59], v[168:171], v[192:195], v[56:59]
	v_mfma_f32_16x16x32_bf16 v[44:47], v[160:163], v[200:203], v[44:47]
	v_mfma_f32_16x16x32_bf16 v[40:43], v[168:171], v[200:203], v[40:43]
	v_mfma_f32_16x16x32_bf16 v[28:31], v[160:163], v[208:211], v[28:31]
	v_mfma_f32_16x16x32_bf16 v[24:27], v[168:171], v[208:211], v[24:27]
	v_mfma_f32_16x16x32_bf16 v[12:15], v[160:163], v[216:219], v[12:15]
	v_mfma_f32_16x16x32_bf16 v[8:11], v[168:171], v[216:219], v[8:11]
	v_mfma_f32_16x16x32_bf16 v[60:63], v[164:167], v[196:199], v[60:63]
	v_mfma_f32_16x16x32_bf16 v[56:59], v[172:175], v[196:199], v[56:59]
	v_mfma_f32_16x16x32_bf16 v[44:47], v[164:167], v[204:207], v[44:47]
	v_mfma_f32_16x16x32_bf16 v[40:43], v[172:175], v[204:207], v[40:43]
	v_mfma_f32_16x16x32_bf16 v[28:31], v[164:167], v[212:215], v[28:31]
	v_mfma_f32_16x16x32_bf16 v[24:27], v[172:175], v[212:215], v[24:27]
	v_mfma_f32_16x16x32_bf16 v[12:15], v[164:167], v[220:223], v[12:15]
	v_mfma_f32_16x16x32_bf16 v[8:11], v[172:175], v[220:223], v[8:11]
	v_mfma_f32_16x16x32_bf16 v[52:55], v[176:179], v[192:195], v[52:55]
	v_mfma_f32_16x16x32_bf16 v[48:51], v[184:187], v[192:195], v[48:51]
	v_mfma_f32_16x16x32_bf16 v[36:39], v[176:179], v[200:203], v[36:39]
	v_mfma_f32_16x16x32_bf16 v[32:35], v[184:187], v[200:203], v[32:35]
	v_mfma_f32_16x16x32_bf16 v[20:23], v[176:179], v[208:211], v[20:23]
	v_mfma_f32_16x16x32_bf16 v[16:19], v[184:187], v[208:211], v[16:19]
	v_mfma_f32_16x16x32_bf16 v[4:7], v[176:179], v[216:219], v[4:7]
	v_mfma_f32_16x16x32_bf16 v[0:3], v[184:187], v[216:219], v[0:3]
	v_mfma_f32_16x16x32_bf16 v[52:55], v[180:183], v[196:199], v[52:55]
	v_mfma_f32_16x16x32_bf16 v[48:51], v[188:191], v[196:199], v[48:51]
	v_mfma_f32_16x16x32_bf16 v[36:39], v[180:183], v[204:207], v[36:39]
	v_mfma_f32_16x16x32_bf16 v[32:35], v[188:191], v[204:207], v[32:35]
	v_mfma_f32_16x16x32_bf16 v[20:23], v[180:183], v[212:215], v[20:23]
	v_mfma_f32_16x16x32_bf16 v[16:19], v[188:191], v[212:215], v[16:19]
	v_mfma_f32_16x16x32_bf16 v[4:7], v[180:183], v[220:223], v[4:7]
	v_mfma_f32_16x16x32_bf16 v[0:3], v[188:191], v[220:223], v[0:3]
	s_setprio 1
	s_barrier
	s_add_i32 s55, 0, 0x18000
	v_add_u32_e32 v141, s55, v147
	s_add_i32 s56, 0, 0x1c000
	ds_read_b128 v[160:163], v141
	ds_read_b128 v[164:167], v141 offset:1024
	ds_read_b128 v[168:171], v141 offset:2048
	ds_read_b128 v[172:175], v141 offset:3072
	v_add_u32_e32 v141, s56, v147
	ds_read_b128 v[176:179], v141
	ds_read_b128 v[180:183], v141 offset:1024
	ds_read_b128 v[184:187], v141 offset:2048
	ds_read_b128 v[188:191], v141 offset:3072
	s_add_u32 s30, s30, 0x80000
	s_addc_u32 s31, s31, 0
	s_mov_b32 m0, s37
	v_lshl_add_u64 v[230:231], s[30:31], 0, v[128:129]
	ds_read_b128 v[192:195], v158 offset:32768
	ds_read_b128 v[196:199], v158 offset:33792
	ds_read_b128 v[200:203], v158 offset:34816
	ds_read_b128 v[204:207], v158 offset:35840
	ds_read_b128 v[208:211], v158 offset:36864
	ds_read_b128 v[212:215], v158 offset:37888
	ds_read_b128 v[216:219], v158 offset:38912
	ds_read_b128 v[220:223], v158 offset:39936
	global_load_lds_dwordx4 v[230:231], off
	v_lshl_add_u64 v[230:231], s[30:31], 0, v[132:133]
	s_mov_b32 m0, s38
	s_nop 0
	global_load_lds_dwordx4 v[230:231], off
	s_waitcnt vmcnt(8)
	s_waitcnt lgkmcnt(0)
	s_barrier
	s_setprio 0
	s_waitcnt lgkmcnt(0)
	v_mfma_f32_16x16x32_bf16 v[124:127], v[160:163], v[192:195], v[124:127]
	v_mfma_f32_16x16x32_bf16 v[120:123], v[168:171], v[192:195], v[120:123]
	v_mfma_f32_16x16x32_bf16 v[108:111], v[160:163], v[200:203], v[108:111]
	v_mfma_f32_16x16x32_bf16 v[104:107], v[168:171], v[200:203], v[104:107]
	v_mfma_f32_16x16x32_bf16 v[92:95], v[160:163], v[208:211], v[92:95]
	v_mfma_f32_16x16x32_bf16 v[88:91], v[168:171], v[208:211], v[88:91]
	v_mfma_f32_16x16x32_bf16 v[76:79], v[160:163], v[216:219], v[76:79]
	v_mfma_f32_16x16x32_bf16 v[72:75], v[168:171], v[216:219], v[72:75]
	v_mfma_f32_16x16x32_bf16 v[124:127], v[164:167], v[196:199], v[124:127]
	v_mfma_f32_16x16x32_bf16 v[120:123], v[172:175], v[196:199], v[120:123]
	v_mfma_f32_16x16x32_bf16 v[108:111], v[164:167], v[204:207], v[108:111]
	v_mfma_f32_16x16x32_bf16 v[104:107], v[172:175], v[204:207], v[104:107]
	v_mfma_f32_16x16x32_bf16 v[92:95], v[164:167], v[212:215], v[92:95]
	v_mfma_f32_16x16x32_bf16 v[88:91], v[172:175], v[212:215], v[88:91]
	v_mfma_f32_16x16x32_bf16 v[76:79], v[164:167], v[220:223], v[76:79]
	v_mfma_f32_16x16x32_bf16 v[72:75], v[172:175], v[220:223], v[72:75]
	v_mfma_f32_16x16x32_bf16 v[116:119], v[176:179], v[192:195], v[116:119]
	v_mfma_f32_16x16x32_bf16 v[112:115], v[184:187], v[192:195], v[112:115]
	v_mfma_f32_16x16x32_bf16 v[100:103], v[176:179], v[200:203], v[100:103]
	v_mfma_f32_16x16x32_bf16 v[96:99], v[184:187], v[200:203], v[96:99]
	v_mfma_f32_16x16x32_bf16 v[84:87], v[176:179], v[208:211], v[84:87]
	v_mfma_f32_16x16x32_bf16 v[80:83], v[184:187], v[208:211], v[80:83]
	v_mfma_f32_16x16x32_bf16 v[68:71], v[176:179], v[216:219], v[68:71]
	v_mfma_f32_16x16x32_bf16 v[64:67], v[184:187], v[216:219], v[64:67]
	v_mfma_f32_16x16x32_bf16 v[116:119], v[180:183], v[196:199], v[116:119]
	v_mfma_f32_16x16x32_bf16 v[112:115], v[188:191], v[196:199], v[112:115]
	v_mfma_f32_16x16x32_bf16 v[100:103], v[180:183], v[204:207], v[100:103]
	v_mfma_f32_16x16x32_bf16 v[96:99], v[188:191], v[204:207], v[96:99]
	v_mfma_f32_16x16x32_bf16 v[84:87], v[180:183], v[212:215], v[84:87]
	v_mfma_f32_16x16x32_bf16 v[80:83], v[188:191], v[212:215], v[80:83]
	v_mfma_f32_16x16x32_bf16 v[68:71], v[180:183], v[220:223], v[68:71]
	v_mfma_f32_16x16x32_bf16 v[64:67], v[188:191], v[220:223], v[64:67]
	s_setprio 1
	s_barrier
; #define PG8_STAGE(bufoff, gbase, voff) do { _Pragma("unroll") for (int _i = 0; _i < 2; ++_i) \
;         __builtin_amdgcn_global_load_lds((const unsigned*)((const char*)(gbase) + (voff)[_i]), (LAS unsigned*)(lds + (bufoff) + ldsw + _i * 8192), 16, 0, 0); } while (0)
; #define PG8_LDA(dst, b, h) do { _Pragma("unroll") for (int m = 0; m < 4; ++m) _Pragma("unroll") for (int k = 0; k < 2; ++k) dst[m][k] = *(const LAS bf16x8*)(lds + PG8_SA(b, h) + aoff + m * 2048 + k * 1024); } while (0)
; #define PG8_MMA(ai, bj, At, Bt) do { __builtin_amdgcn_s_setprio(1); _Pragma("unroll") for (int m = 0; m < 4; ++m) _Pragma("unroll") for (int n = 0; n < 2; ++n) _Pragma("unroll") for (int k = 0; k < 2; ++k) \
;         acc[ai][bj][m][n] = __builtin_amdgcn_mfma_f32_16x16x32_bf16(Bt[n][k], At[m][k], acc[ai][bj][m][n], 0, 0, 0); __builtin_amdgcn_s_setprio(0); } while (0)
; #define PG8_WAIT_V(n) asm volatile("s_waitcnt vmcnt(" #n ")" ::: "memory")
; #define PG8_WAIT_L(n) asm volatile("s_waitcnt lgkmcnt(" #n ")" ::: "memory")
; #define PG8_BAR __builtin_amdgcn_s_barrier()
; #define PG8_SCHED __builtin_amdgcn_sched_barrier(0)
; __device__ __forceinline__ void gemm_phase(LAS unsigned char* lds, const Params& p, const bf16_t* gA, const bf16_t* gBt, const int gM, const int gN, const int gK, const int epi, const int perm, bf16_t* const Hp, const int goff, const float coef) {
;     ...
;             PG8_LDA(At, 1, 1); PG8_STAGE(PG8_SB(1, 0), b3, voffB); PG8_STAGE(PG8_SB(1, 1), b3 + hstep, voffB); PG8_STAGE(PG8_SA(1, 0), a3, voffA);
;             PG8_WAIT_V(8); PG8_WAIT_L(0); PG8_BAR; PG8_MMA(1, 0, At, B0); PG8_MMA(1, 1, At, B1); PG8_BAR; PG8_SCHED;
;         }
;         if (wr == 0) PG8_BAR;
	s_add_i32 s30, s55, s36
	v_lshl_add_u64 v[144:145], v[144:145], 0, s[8:9]
	s_mov_b32 m0, s30
	ds_read_b128 v[192:195], v158 offset:49152
	ds_read_b128 v[196:199], v158 offset:50176
	ds_read_b128 v[200:203], v158 offset:51200
	ds_read_b128 v[204:207], v158 offset:52224
	ds_read_b128 v[208:211], v158 offset:53248
	ds_read_b128 v[212:215], v158 offset:54272
	ds_read_b128 v[216:219], v158 offset:55296
	ds_read_b128 v[220:223], v158 offset:56320
	global_load_lds_dwordx4 v[144:145], off
	s_add_i32 m0, s30, 0x2000
	s_add_u32 s28, s28, 0x80080
	v_lshl_add_u64 v[144:145], v[224:225], 0, s[8:9]
	s_addc_u32 s29, s29, 0
	s_add_i32 s30, s56, s36
	global_load_lds_dwordx4 v[144:145], off
	v_lshl_add_u64 v[144:145], s[28:29], 0, v[130:131]
	s_mov_b32 m0, s30
	s_nop 0
	global_load_lds_dwordx4 v[144:145], off
	v_lshl_add_u64 v[144:145], s[28:29], 0, v[134:135]
	s_add_i32 m0, s30, 0x2000
	s_nop 0
	global_load_lds_dwordx4 v[144:145], off
	v_lshl_add_u64 v[144:145], v[226:227], 0, s[8:9]
	s_mov_b32 m0, s40
	s_nop 0
	global_load_lds_dwordx4 v[144:145], off
	v_lshl_add_u64 v[144:145], v[228:229], 0, s[8:9]
	s_mov_b32 m0, s41
	s_nop 0
	global_load_lds_dwordx4 v[144:145], off
	s_waitcnt vmcnt(8)
	s_waitcnt lgkmcnt(0)
	s_barrier
	s_setprio 0
	s_waitcnt lgkmcnt(0)
	v_mfma_f32_16x16x32_bf16 v[60:63], v[160:163], v[192:195], v[60:63]
	v_mfma_f32_16x16x32_bf16 v[56:59], v[168:171], v[192:195], v[56:59]
	v_mfma_f32_16x16x32_bf16 v[44:47], v[160:163], v[200:203], v[44:47]
	v_mfma_f32_16x16x32_bf16 v[40:43], v[168:171], v[200:203], v[40:43]
	v_mfma_f32_16x16x32_bf16 v[28:31], v[160:163], v[208:211], v[28:31]
	v_mfma_f32_16x16x32_bf16 v[24:27], v[168:171], v[208:211], v[24:27]
	v_mfma_f32_16x16x32_bf16 v[12:15], v[160:163], v[216:219], v[12:15]
	v_mfma_f32_16x16x32_bf16 v[8:11], v[168:171], v[216:219], v[8:11]
	v_mfma_f32_16x16x32_bf16 v[60:63], v[164:167], v[196:199], v[60:63]
	v_mfma_f32_16x16x32_bf16 v[56:59], v[172:175], v[196:199], v[56:59]
	v_mfma_f32_16x16x32_bf16 v[44:47], v[164:167], v[204:207], v[44:47]
	v_mfma_f32_16x16x32_bf16 v[40:43], v[172:175], v[204:207], v[40:43]
	v_mfma_f32_16x16x32_bf16 v[28:31], v[164:167], v[212:215], v[28:31]
	v_mfma_f32_16x16x32_bf16 v[24:27], v[172:175], v[212:215], v[24:27]
	v_mfma_f32_16x16x32_bf16 v[12:15], v[164:167], v[220:223], v[12:15]
	v_mfma_f32_16x16x32_bf16 v[8:11], v[172:175], v[220:223], v[8:11]
	v_mfma_f32_16x16x32_bf16 v[52:55], v[176:179], v[192:195], v[52:55]
	v_mfma_f32_16x16x32_bf16 v[48:51], v[184:187], v[192:195], v[48:51]
	v_mfma_f32_16x16x32_bf16 v[36:39], v[176:179], v[200:203], v[36:39]
	v_mfma_f32_16x16x32_bf16 v[32:35], v[184:187], v[200:203], v[32:35]
	v_mfma_f32_16x16x32_bf16 v[20:23], v[176:179], v[208:211], v[20:23]
	v_mfma_f32_16x16x32_bf16 v[16:19], v[184:187], v[208:211], v[16:19]
	v_mfma_f32_16x16x32_bf16 v[4:7], v[176:179], v[216:219], v[4:7]
	v_mfma_f32_16x16x32_bf16 v[0:3], v[184:187], v[216:219], v[0:3]
	v_mfma_f32_16x16x32_bf16 v[52:55], v[180:183], v[196:199], v[52:55]
	v_mfma_f32_16x16x32_bf16 v[48:51], v[188:191], v[196:199], v[48:51]
	v_mfma_f32_16x16x32_bf16 v[36:39], v[180:183], v[204:207], v[36:39]
	v_mfma_f32_16x16x32_bf16 v[32:35], v[188:191], v[204:207], v[32:35]
	v_mfma_f32_16x16x32_bf16 v[20:23], v[180:183], v[212:215], v[20:23]
	v_mfma_f32_16x16x32_bf16 v[16:19], v[188:191], v[212:215], v[16:19]
	v_mfma_f32_16x16x32_bf16 v[4:7], v[180:183], v[220:223], v[4:7]
	v_mfma_f32_16x16x32_bf16 v[0:3], v[188:191], v[220:223], v[0:3]
	s_setprio 1
	s_barrier
	s_add_u32 s26, s26, 0x100
	s_addc_u32 s27, s27, 0
	s_add_u32 s52, s52, 0x100
	s_addc_u32 s53, s53, 0
	s_cmp_ge_u32 s54, s50
	s_mov_b32 s30, s54
	s_cbranch_scc0 .LBB0_1737
	s_and_b64 vcc, exec, s[10:11]
	s_cbranch_vccz .LBB0_1740
	s_barrier

; #define PG8_STAGE(bufoff, gbase, voff) do { _Pragma("unroll") for (int _i = 0; _i < 2; ++_i) \
;         __builtin_amdgcn_global_load_lds((const unsigned*)((const char*)(gbase) + (voff)[_i]), (LAS unsigned*)(lds + (bufoff) + ldsw + _i * 8192), 16, 0, 0); } while (0)
; #define PG8_LDA(dst, b, h) do { _Pragma("unroll") for (int m = 0; m < 4; ++m) _Pragma("unroll") for (int k = 0; k < 2; ++k) dst[m][k] = *(const LAS bf16x8*)(lds + PG8_SA(b, h) + aoff + m * 2048 + k * 1024); } while (0)
; #define PG8_LDB(dst, b, h) do { _Pragma("unroll") for (int n = 0; n < 2; ++n) _Pragma("unroll") for (int k = 0; k < 2; ++k) dst[n][k] = *(const LAS bf16x8*)(lds + PG8_SB(b, h) + boff + n * 2048 + k * 1024); } while (0)
; #define PG8_MMA(ai, bj, At, Bt) do { __builtin_amdgcn_s_setprio(1); _Pragma("unroll") for (int m = 0; m < 4; ++m) _Pragma("unroll") for (int n = 0; n < 2; ++n) _Pragma("unroll") for (int k = 0; k < 2; ++k) \
;         acc[ai][bj][m][n] = __builtin_amdgcn_mfma_f32_16x16x32_bf16(Bt[n][k], At[m][k], acc[ai][bj][m][n], 0, 0, 0); __builtin_amdgcn_s_setprio(0); } while (0)
; #define PG8_WAIT_V(n) asm volatile("s_waitcnt vmcnt(" #n ")" ::: "memory")
; #define PG8_WAIT_L(n) asm volatile("s_waitcnt lgkmcnt(" #n ")" ::: "memory")
; __device__ __forceinline__ void gemm_phase(LAS unsigned char* lds, const Params& p, const bf16_t* gA, const bf16_t* gBt, const int gM, const int gN, const int gK, const int epi, const int perm, bf16_t* const Hp, const int goff, const float coef) {
;     ...
;         for (int t = 0; t < nt; t += 2) {
;             const bool last = (t == nt - 2);
;             const char* a1 = cA + (size_t)(t + 1) * kstep;
;             const char* a2 = last ? nA : cA + (size_t)(t + 2) * kstep; const char* b2 = last ? nB : cB + (size_t)(t + 2) * kstep;
;             const char* a3 = a2 + kstep; const char* b3 = b2 + kstep;
;             PG8_LDB(B0, 0, 0); PG8_LDB(B1, 0, 1); PG8_SCHED; PG8_LDA(At, 0, 0); PG8_STAGE(PG8_SA(1, 1), a1 + hstep, voffA);
;             PG8_WAIT_V(8); PG8_WAIT_L(0); PG8_BAR; PG8_MMA(0, 0, At, B0); PG8_MMA(0, 1, At, B1); PG8_BAR; PG8_SCHED;
;             PG8_LDA(At, 0, 1); PG8_STAGE(PG8_SB(0, 0), b2, voffB); PG8_STAGE(PG8_SB(0, 1), b2 + hstep, voffB); PG8_STAGE(PG8_SA(0, 0), a2, voffA);
;             PG8_WAIT_V(8); PG8_WAIT_L(0); PG8_BAR; PG8_MMA(1, 0, At, B0); PG8_MMA(1, 1, At, B1); PG8_BAR; PG8_SCHED;
.LBB0_1827:
	ds_read_b128 v[144:147], v166
	ds_read_b128 v[148:151], v166 offset:1024
	ds_read_b128 v[152:155], v166 offset:2048
	ds_read_b128 v[170:173], v166 offset:3072
	ds_read_b128 v[174:177], v167
	ds_read_b128 v[178:181], v167 offset:1024
	ds_read_b128 v[182:185], v167 offset:2048
	ds_read_b128 v[186:189], v167 offset:3072
	s_add_i32 s54, s20, 2
	s_add_u32 s21, s18, 0xffea0080
	s_addc_u32 s22, s19, -1
	s_cmp_eq_u32 s51, s20
	s_cselect_b32 s20, s16, s52
	s_cselect_b32 s23, s15, s22
	s_cselect_b32 s22, s14, s21
	s_cselect_b32 s21, s17, s53
	v_lshl_add_u64 v[222:223], s[18:19], 0, v[136:137]
	s_add_i32 m0, s28, 0xc000
	ds_read_b128 v[190:193], v168
	ds_read_b128 v[194:197], v168 offset:1024
	ds_read_b128 v[198:201], v168 offset:2048
	ds_read_b128 v[202:205], v168 offset:3072
	ds_read_b128 v[206:209], v168 offset:4096
	ds_read_b128 v[210:213], v168 offset:5120
	ds_read_b128 v[214:217], v168 offset:6144
	ds_read_b128 v[218:221], v168 offset:7168
	global_load_lds_dwordx4 v[222:223], off
	v_lshl_add_u64 v[222:223], s[18:19], 0, v[138:139]
	s_add_i32 m0, s28, 0xe000
	s_nop 0
	global_load_lds_dwordx4 v[222:223], off
	s_waitcnt vmcnt(8)
	s_waitcnt lgkmcnt(0)
	s_barrier
	s_setprio 0
	s_waitcnt lgkmcnt(0)
	v_mfma_f32_16x16x32_bf16 v[124:127], v[144:147], v[190:193], v[124:127]
	v_mfma_f32_16x16x32_bf16 v[120:123], v[152:155], v[190:193], v[120:123]
	v_mfma_f32_16x16x32_bf16 v[116:119], v[144:147], v[198:201], v[116:119]
	v_mfma_f32_16x16x32_bf16 v[112:115], v[152:155], v[198:201], v[112:115]
	v_mfma_f32_16x16x32_bf16 v[108:111], v[144:147], v[206:209], v[108:111]
	v_mfma_f32_16x16x32_bf16 v[104:107], v[152:155], v[206:209], v[104:107]
	v_mfma_f32_16x16x32_bf16 v[100:103], v[144:147], v[214:217], v[100:103]
	v_mfma_f32_16x16x32_bf16 v[96:99], v[152:155], v[214:217], v[96:99]
	v_mfma_f32_16x16x32_bf16 v[124:127], v[148:151], v[194:197], v[124:127]
	v_mfma_f32_16x16x32_bf16 v[120:123], v[170:173], v[194:197], v[120:123]
	v_mfma_f32_16x16x32_bf16 v[116:119], v[148:151], v[202:205], v[116:119]
	v_mfma_f32_16x16x32_bf16 v[112:115], v[170:173], v[202:205], v[112:115]
	v_mfma_f32_16x16x32_bf16 v[108:111], v[148:151], v[210:213], v[108:111]
	v_mfma_f32_16x16x32_bf16 v[104:107], v[170:173], v[210:213], v[104:107]
	v_mfma_f32_16x16x32_bf16 v[100:103], v[148:151], v[218:221], v[100:103]
	v_mfma_f32_16x16x32_bf16 v[96:99], v[170:173], v[218:221], v[96:99]
	v_mfma_f32_16x16x32_bf16 v[68:71], v[174:177], v[190:193], v[68:71]
	v_mfma_f32_16x16x32_bf16 v[60:63], v[182:185], v[190:193], v[60:63]
	v_mfma_f32_16x16x32_bf16 v[52:55], v[174:177], v[198:201], v[52:55]
	v_mfma_f32_16x16x32_bf16 v[48:51], v[182:185], v[198:201], v[48:51]
	v_mfma_f32_16x16x32_bf16 v[44:47], v[174:177], v[206:209], v[44:47]
	v_mfma_f32_16x16x32_bf16 v[40:43], v[182:185], v[206:209], v[40:43]
	v_mfma_f32_16x16x32_bf16 v[36:39], v[174:177], v[214:217], v[36:39]
	v_mfma_f32_16x16x32_bf16 v[32:35], v[182:185], v[214:217], v[32:35]
	v_mfma_f32_16x16x32_bf16 v[68:71], v[178:181], v[194:197], v[68:71]
	v_mfma_f32_16x16x32_bf16 v[60:63], v[186:189], v[194:197], v[60:63]
	v_mfma_f32_16x16x32_bf16 v[52:55], v[178:181], v[202:205], v[52:55]
	v_mfma_f32_16x16x32_bf16 v[48:51], v[186:189], v[202:205], v[48:51]
	v_mfma_f32_16x16x32_bf16 v[44:47], v[178:181], v[210:213], v[44:47]
	v_mfma_f32_16x16x32_bf16 v[40:43], v[186:189], v[210:213], v[40:43]
	v_mfma_f32_16x16x32_bf16 v[36:39], v[178:181], v[218:221], v[36:39]
	v_mfma_f32_16x16x32_bf16 v[32:35], v[186:189], v[218:221], v[32:35]
	s_setprio 1
	s_barrier
	s_add_i32 s55, s42, s27
	v_lshl_add_u64 v[222:223], s[20:21], 0, v[130:131]
	s_mov_b32 m0, s55
	ds_read_b128 v[190:193], v168 offset:16384
	ds_read_b128 v[194:197], v168 offset:17408
	ds_read_b128 v[198:201], v168 offset:18432
	ds_read_b128 v[202:205], v168 offset:19456
	ds_read_b128 v[206:209], v168 offset:20480
	ds_read_b128 v[210:213], v168 offset:21504
	ds_read_b128 v[214:217], v168 offset:22528
	ds_read_b128 v[218:221], v168 offset:23552
	global_load_lds_dwordx4 v[222:223], off
	s_add_i32 m0, s55, 0x2000
	s_add_u32 s56, s20, 0x160000
	v_lshl_add_u64 v[224:225], s[20:21], 0, v[134:135]
	s_addc_u32 s57, s21, 0
	s_add_i32 s55, s43, s27
	global_load_lds_dwordx4 v[224:225], off
	v_lshl_add_u64 v[226:227], s[56:57], 0, v[130:131]
	s_mov_b32 m0, s55
	v_lshl_add_u64 v[228:229], s[22:23], 0, v[132:133]
	global_load_lds_dwordx4 v[226:227], off
	v_lshl_add_u64 v[226:227], s[56:57], 0, v[134:135]
	s_add_i32 m0, s55, 0x2000
	s_nop 0
	global_load_lds_dwordx4 v[226:227], off
	v_lshl_add_u64 v[226:227], s[22:23], 0, v[128:129]
	s_mov_b32 m0, s28
	s_nop 0
	global_load_lds_dwordx4 v[226:227], off
	s_mov_b32 m0, s29
	s_nop 0
	global_load_lds_dwordx4 v[228:229], off
	s_waitcnt vmcnt(8)
	s_waitcnt lgkmcnt(0)
	s_barrier
; #define PG8_STAGE(bufoff, gbase, voff) do { _Pragma("unroll") for (int _i = 0; _i < 2; ++_i) \
;         __builtin_amdgcn_global_load_lds((const unsigned*)((const char*)(gbase) + (voff)[_i]), (LAS unsigned*)(lds + (bufoff) + ldsw + _i * 8192), 16, 0, 0); } while (0)
; #define PG8_LDA(dst, b, h) do { _Pragma("unroll") for (int m = 0; m < 4; ++m) _Pragma("unroll") for (int k = 0; k < 2; ++k) dst[m][k] = *(const LAS bf16x8*)(lds + PG8_SA(b, h) + aoff + m * 2048 + k * 1024); } while (0)
; #define PG8_LDB(dst, b, h) do { _Pragma("unroll") for (int n = 0; n < 2; ++n) _Pragma("unroll") for (int k = 0; k < 2; ++k) dst[n][k] = *(const LAS bf16x8*)(lds + PG8_SB(b, h) + boff + n * 2048 + k * 1024); } while (0)
; #define PG8_MMA(ai, bj, At, Bt) do { __builtin_amdgcn_s_setprio(1); _Pragma("unroll") for (int m = 0; m < 4; ++m) _Pragma("unroll") for (int n = 0; n < 2; ++n) _Pragma("unroll") for (int k = 0; k < 2; ++k) \
;         acc[ai][bj][m][n] = __builtin_amdgcn_mfma_f32_16x16x32_bf16(Bt[n][k], At[m][k], acc[ai][bj][m][n], 0, 0, 0); __builtin_amdgcn_s_setprio(0); } while (0)
; #define PG8_WAIT_V(n) asm volatile("s_waitcnt vmcnt(" #n ")" ::: "memory")
; #define PG8_WAIT_L(n) asm volatile("s_waitcnt lgkmcnt(" #n ")" ::: "memory")
; #define PG8_BAR __builtin_amdgcn_s_barrier()
; #define PG8_SCHED __builtin_amdgcn_sched_barrier(0)
; __device__ __forceinline__ void gemm_phase(LAS unsigned char* lds, const Params& p, const bf16_t* gA, const bf16_t* gBt, const int gM, const int gN, const int gK, const int epi, const int perm, bf16_t* const Hp, const int goff, const float coef) {
;     ...
;             PG8_WAIT_V(8); PG8_WAIT_L(0); PG8_BAR; PG8_MMA(1, 0, At, B0); PG8_MMA(1, 1, At, B1); PG8_BAR; PG8_SCHED;
;             PG8_LDB(B0, 1, 0); PG8_LDB(B1, 1, 1); PG8_SCHED; PG8_LDA(At, 1, 0); PG8_STAGE(PG8_SA(0, 1), a2 + hstep, voffA);
;             PG8_WAIT_V(8); PG8_WAIT_L(0); PG8_BAR; PG8_MMA(0, 0, At, B0); PG8_MMA(0, 1, At, B1); PG8_BAR; PG8_SCHED;
	s_setprio 0
	s_waitcnt lgkmcnt(0)
	v_mfma_f32_16x16x32_bf16 v[92:95], v[144:147], v[190:193], v[92:95]
	v_mfma_f32_16x16x32_bf16 v[88:91], v[152:155], v[190:193], v[88:91]
	v_mfma_f32_16x16x32_bf16 v[84:87], v[144:147], v[198:201], v[84:87]
	v_mfma_f32_16x16x32_bf16 v[80:83], v[152:155], v[198:201], v[80:83]
	v_mfma_f32_16x16x32_bf16 v[76:79], v[144:147], v[206:209], v[76:79]
	v_mfma_f32_16x16x32_bf16 v[72:75], v[152:155], v[206:209], v[72:75]
	v_mfma_f32_16x16x32_bf16 v[64:67], v[144:147], v[214:217], v[64:67]
	v_mfma_f32_16x16x32_bf16 v[56:59], v[152:155], v[214:217], v[56:59]
	v_mfma_f32_16x16x32_bf16 v[92:95], v[148:151], v[194:197], v[92:95]
	v_mfma_f32_16x16x32_bf16 v[88:91], v[170:173], v[194:197], v[88:91]
	v_mfma_f32_16x16x32_bf16 v[84:87], v[148:151], v[202:205], v[84:87]
	v_mfma_f32_16x16x32_bf16 v[80:83], v[170:173], v[202:205], v[80:83]
	v_mfma_f32_16x16x32_bf16 v[76:79], v[148:151], v[210:213], v[76:79]
	v_mfma_f32_16x16x32_bf16 v[72:75], v[170:173], v[210:213], v[72:75]
	v_mfma_f32_16x16x32_bf16 v[64:67], v[148:151], v[218:221], v[64:67]
	v_mfma_f32_16x16x32_bf16 v[56:59], v[170:173], v[218:221], v[56:59]
	v_mfma_f32_16x16x32_bf16 v[28:31], v[174:177], v[190:193], v[28:31]
	v_mfma_f32_16x16x32_bf16 v[24:27], v[182:185], v[190:193], v[24:27]
	v_mfma_f32_16x16x32_bf16 v[20:23], v[174:177], v[198:201], v[20:23]
	v_mfma_f32_16x16x32_bf16 v[16:19], v[182:185], v[198:201], v[16:19]
	v_mfma_f32_16x16x32_bf16 v[12:15], v[174:177], v[206:209], v[12:15]
	v_mfma_f32_16x16x32_bf16 v[8:11], v[182:185], v[206:209], v[8:11]
	v_mfma_f32_16x16x32_bf16 v[4:7], v[174:177], v[214:217], v[4:7]
	v_mfma_f32_16x16x32_bf16 v[0:3], v[182:185], v[214:217], v[0:3]
	v_mfma_f32_16x16x32_bf16 v[28:31], v[178:181], v[194:197], v[28:31]
	v_mfma_f32_16x16x32_bf16 v[24:27], v[186:189], v[194:197], v[24:27]
	v_mfma_f32_16x16x32_bf16 v[20:23], v[178:181], v[202:205], v[20:23]
	v_mfma_f32_16x16x32_bf16 v[16:19], v[186:189], v[202:205], v[16:19]
	v_mfma_f32_16x16x32_bf16 v[12:15], v[178:181], v[210:213], v[12:15]
	v_mfma_f32_16x16x32_bf16 v[8:11], v[186:189], v[210:213], v[8:11]
	v_mfma_f32_16x16x32_bf16 v[4:7], v[178:181], v[218:221], v[4:7]
	v_mfma_f32_16x16x32_bf16 v[0:3], v[186:189], v[218:221], v[0:3]
	s_setprio 1
	s_barrier
	s_add_i32 s55, 0, 0x18000
	v_add_u32_e32 v141, s55, v157
	s_add_i32 s56, 0, 0x1c000
	ds_read_b128 v[144:147], v141
	ds_read_b128 v[148:151], v141 offset:1024
	ds_read_b128 v[152:155], v141 offset:2048
	ds_read_b128 v[170:173], v141 offset:3072
	v_add_u32_e32 v141, s56, v157
	ds_read_b128 v[174:177], v141
	ds_read_b128 v[178:181], v141 offset:1024
	ds_read_b128 v[182:185], v141 offset:2048
	ds_read_b128 v[186:189], v141 offset:3072
	s_add_u32 s22, s22, 0x160000
	s_addc_u32 s23, s23, 0
	s_mov_b32 m0, s30
	v_lshl_add_u64 v[230:231], s[22:23], 0, v[128:129]
	ds_read_b128 v[190:193], v168 offset:32768
	ds_read_b128 v[194:197], v168 offset:33792
	ds_read_b128 v[198:201], v168 offset:34816
	ds_read_b128 v[202:205], v168 offset:35840
	ds_read_b128 v[206:209], v168 offset:36864
	ds_read_b128 v[210:213], v168 offset:37888
	ds_read_b128 v[214:217], v168 offset:38912
	ds_read_b128 v[218:221], v168 offset:39936
	global_load_lds_dwordx4 v[230:231], off
	v_lshl_add_u64 v[230:231], s[22:23], 0, v[132:133]
	s_mov_b32 m0, s31
	s_nop 0
	global_load_lds_dwordx4 v[230:231], off
	s_waitcnt vmcnt(8)
	s_waitcnt lgkmcnt(0)
	s_barrier
	s_setprio 0
	s_waitcnt lgkmcnt(0)
	v_mfma_f32_16x16x32_bf16 v[124:127], v[144:147], v[190:193], v[124:127]
	v_mfma_f32_16x16x32_bf16 v[120:123], v[152:155], v[190:193], v[120:123]
	v_mfma_f32_16x16x32_bf16 v[116:119], v[144:147], v[198:201], v[116:119]
	v_mfma_f32_16x16x32_bf16 v[112:115], v[152:155], v[198:201], v[112:115]
	v_mfma_f32_16x16x32_bf16 v[108:111], v[144:147], v[206:209], v[108:111]
	v_mfma_f32_16x16x32_bf16 v[104:107], v[152:155], v[206:209], v[104:107]
	v_mfma_f32_16x16x32_bf16 v[100:103], v[144:147], v[214:217], v[100:103]
	v_mfma_f32_16x16x32_bf16 v[96:99], v[152:155], v[214:217], v[96:99]
	v_mfma_f32_16x16x32_bf16 v[124:127], v[148:151], v[194:197], v[124:127]
	v_mfma_f32_16x16x32_bf16 v[120:123], v[170:173], v[194:197], v[120:123]
	v_mfma_f32_16x16x32_bf16 v[116:119], v[148:151], v[202:205], v[116:119]
	v_mfma_f32_16x16x32_bf16 v[112:115], v[170:173], v[202:205], v[112:115]
	v_mfma_f32_16x16x32_bf16 v[108:111], v[148:151], v[210:213], v[108:111]
	v_mfma_f32_16x16x32_bf16 v[104:107], v[170:173], v[210:213], v[104:107]
	v_mfma_f32_16x16x32_bf16 v[100:103], v[148:151], v[218:221], v[100:103]
	v_mfma_f32_16x16x32_bf16 v[96:99], v[170:173], v[218:221], v[96:99]
	v_mfma_f32_16x16x32_bf16 v[68:71], v[174:177], v[190:193], v[68:71]
	v_mfma_f32_16x16x32_bf16 v[60:63], v[182:185], v[190:193], v[60:63]
	v_mfma_f32_16x16x32_bf16 v[52:55], v[174:177], v[198:201], v[52:55]
	v_mfma_f32_16x16x32_bf16 v[48:51], v[182:185], v[198:201], v[48:51]
	v_mfma_f32_16x16x32_bf16 v[44:47], v[174:177], v[206:209], v[44:47]
	v_mfma_f32_16x16x32_bf16 v[40:43], v[182:185], v[206:209], v[40:43]
	v_mfma_f32_16x16x32_bf16 v[36:39], v[174:177], v[214:217], v[36:39]
	v_mfma_f32_16x16x32_bf16 v[32:35], v[182:185], v[214:217], v[32:35]
	v_mfma_f32_16x16x32_bf16 v[68:71], v[178:181], v[194:197], v[68:71]
	v_mfma_f32_16x16x32_bf16 v[60:63], v[186:189], v[194:197], v[60:63]
	v_mfma_f32_16x16x32_bf16 v[52:55], v[178:181], v[202:205], v[52:55]
	v_mfma_f32_16x16x32_bf16 v[48:51], v[186:189], v[202:205], v[48:51]
	v_mfma_f32_16x16x32_bf16 v[44:47], v[178:181], v[210:213], v[44:47]
	v_mfma_f32_16x16x32_bf16 v[40:43], v[186:189], v[210:213], v[40:43]
	v_mfma_f32_16x16x32_bf16 v[36:39], v[178:181], v[218:221], v[36:39]
	v_mfma_f32_16x16x32_bf16 v[32:35], v[186:189], v[218:221], v[32:35]
	s_setprio 1
	s_barrier
; #define PG8_STAGE(bufoff, gbase, voff) do { _Pragma("unroll") for (int _i = 0; _i < 2; ++_i) \
;         __builtin_amdgcn_global_load_lds((const unsigned*)((const char*)(gbase) + (voff)[_i]), (LAS unsigned*)(lds + (bufoff) + ldsw + _i * 8192), 16, 0, 0); } while (0)
; #define PG8_LDA(dst, b, h) do { _Pragma("unroll") for (int m = 0; m < 4; ++m) _Pragma("unroll") for (int k = 0; k < 2; ++k) dst[m][k] = *(const LAS bf16x8*)(lds + PG8_SA(b, h) + aoff + m * 2048 + k * 1024); } while (0)
; #define PG8_MMA(ai, bj, At, Bt) do { __builtin_amdgcn_s_setprio(1); _Pragma("unroll") for (int m = 0; m < 4; ++m) _Pragma("unroll") for (int n = 0; n < 2; ++n) _Pragma("unroll") for (int k = 0; k < 2; ++k) \
;         acc[ai][bj][m][n] = __builtin_amdgcn_mfma_f32_16x16x32_bf16(Bt[n][k], At[m][k], acc[ai][bj][m][n], 0, 0, 0); __builtin_amdgcn_s_setprio(0); } while (0)
; #define PG8_WAIT_V(n) asm volatile("s_waitcnt vmcnt(" #n ")" ::: "memory")
; #define PG8_WAIT_L(n) asm volatile("s_waitcnt lgkmcnt(" #n ")" ::: "memory")
; #define PG8_BAR __builtin_amdgcn_s_barrier()
; #define PG8_SCHED __builtin_amdgcn_sched_barrier(0)
; __device__ __forceinline__ void gemm_phase(LAS unsigned char* lds, const Params& p, const bf16_t* gA, const bf16_t* gBt, const int gM, const int gN, const int gK, const int epi, const int perm, bf16_t* const Hp, const int goff, const float coef) {
;     ...
;             PG8_LDA(At, 1, 1); PG8_STAGE(PG8_SB(1, 0), b3, voffB); PG8_STAGE(PG8_SB(1, 1), b3 + hstep, voffB); PG8_STAGE(PG8_SA(1, 0), a3, voffA);
;             PG8_WAIT_V(8); PG8_WAIT_L(0); PG8_BAR; PG8_MMA(1, 0, At, B0); PG8_MMA(1, 1, At, B1); PG8_BAR; PG8_SCHED;
;         }
;         if (wr == 0) PG8_BAR;
	s_add_i32 s22, s55, s27
	v_lshl_add_u64 v[222:223], v[222:223], 0, s[10:11]
	s_mov_b32 m0, s22
	ds_read_b128 v[190:193], v168 offset:49152
	ds_read_b128 v[194:197], v168 offset:50176
	ds_read_b128 v[198:201], v168 offset:51200
	ds_read_b128 v[202:205], v168 offset:52224
	ds_read_b128 v[206:209], v168 offset:53248
	ds_read_b128 v[210:213], v168 offset:54272
	ds_read_b128 v[214:217], v168 offset:55296
	ds_read_b128 v[218:221], v168 offset:56320
	global_load_lds_dwordx4 v[222:223], off
	s_add_i32 m0, s22, 0x2000
	s_add_u32 s20, s20, 0x160080
	v_lshl_add_u64 v[222:223], v[224:225], 0, s[10:11]
	s_addc_u32 s21, s21, 0
	s_add_i32 s22, s56, s27
	global_load_lds_dwordx4 v[222:223], off
	v_lshl_add_u64 v[222:223], s[20:21], 0, v[130:131]
	s_mov_b32 m0, s22
	s_nop 0
	global_load_lds_dwordx4 v[222:223], off
	v_lshl_add_u64 v[222:223], s[20:21], 0, v[134:135]
	s_add_i32 m0, s22, 0x2000
	s_nop 0
	global_load_lds_dwordx4 v[222:223], off
	v_lshl_add_u64 v[222:223], v[226:227], 0, s[10:11]
	s_mov_b32 m0, s36
	s_nop 0
	global_load_lds_dwordx4 v[222:223], off
	v_lshl_add_u64 v[222:223], v[228:229], 0, s[10:11]
	s_mov_b32 m0, s37
	s_nop 0
	global_load_lds_dwordx4 v[222:223], off
	s_waitcnt vmcnt(8)
	s_waitcnt lgkmcnt(0)
	s_barrier
	s_setprio 0
	s_waitcnt lgkmcnt(0)
	v_mfma_f32_16x16x32_bf16 v[92:95], v[144:147], v[190:193], v[92:95]
	v_mfma_f32_16x16x32_bf16 v[88:91], v[152:155], v[190:193], v[88:91]
	v_mfma_f32_16x16x32_bf16 v[84:87], v[144:147], v[198:201], v[84:87]
	v_mfma_f32_16x16x32_bf16 v[80:83], v[152:155], v[198:201], v[80:83]
	v_mfma_f32_16x16x32_bf16 v[76:79], v[144:147], v[206:209], v[76:79]
	v_mfma_f32_16x16x32_bf16 v[72:75], v[152:155], v[206:209], v[72:75]
	v_mfma_f32_16x16x32_bf16 v[64:67], v[144:147], v[214:217], v[64:67]
	v_mfma_f32_16x16x32_bf16 v[56:59], v[152:155], v[214:217], v[56:59]
	v_mfma_f32_16x16x32_bf16 v[92:95], v[148:151], v[194:197], v[92:95]
	v_mfma_f32_16x16x32_bf16 v[88:91], v[170:173], v[194:197], v[88:91]
	v_mfma_f32_16x16x32_bf16 v[84:87], v[148:151], v[202:205], v[84:87]
	v_mfma_f32_16x16x32_bf16 v[80:83], v[170:173], v[202:205], v[80:83]
	v_mfma_f32_16x16x32_bf16 v[76:79], v[148:151], v[210:213], v[76:79]
	v_mfma_f32_16x16x32_bf16 v[72:75], v[170:173], v[210:213], v[72:75]
	v_mfma_f32_16x16x32_bf16 v[64:67], v[148:151], v[218:221], v[64:67]
	v_mfma_f32_16x16x32_bf16 v[56:59], v[170:173], v[218:221], v[56:59]
	v_mfma_f32_16x16x32_bf16 v[28:31], v[174:177], v[190:193], v[28:31]
	v_mfma_f32_16x16x32_bf16 v[24:27], v[182:185], v[190:193], v[24:27]
	v_mfma_f32_16x16x32_bf16 v[20:23], v[174:177], v[198:201], v[20:23]
	v_mfma_f32_16x16x32_bf16 v[16:19], v[182:185], v[198:201], v[16:19]
	v_mfma_f32_16x16x32_bf16 v[12:15], v[174:177], v[206:209], v[12:15]
	v_mfma_f32_16x16x32_bf16 v[8:11], v[182:185], v[206:209], v[8:11]
	v_mfma_f32_16x16x32_bf16 v[4:7], v[174:177], v[214:217], v[4:7]
	v_mfma_f32_16x16x32_bf16 v[0:3], v[182:185], v[214:217], v[0:3]
	v_mfma_f32_16x16x32_bf16 v[28:31], v[178:181], v[194:197], v[28:31]
	v_mfma_f32_16x16x32_bf16 v[24:27], v[186:189], v[194:197], v[24:27]
	v_mfma_f32_16x16x32_bf16 v[20:23], v[178:181], v[202:205], v[20:23]
	v_mfma_f32_16x16x32_bf16 v[16:19], v[186:189], v[202:205], v[16:19]
	v_mfma_f32_16x16x32_bf16 v[12:15], v[178:181], v[210:213], v[12:15]
	v_mfma_f32_16x16x32_bf16 v[8:11], v[186:189], v[210:213], v[8:11]
	v_mfma_f32_16x16x32_bf16 v[4:7], v[178:181], v[218:221], v[4:7]
	v_mfma_f32_16x16x32_bf16 v[0:3], v[186:189], v[218:221], v[0:3]
	s_setprio 1
	s_barrier
	s_add_u32 s18, s18, 0x100
	s_addc_u32 s19, s19, 0
	s_add_u32 s52, s52, 0x100
	s_addc_u32 s53, s53, 0
	s_cmp_ge_u32 s54, s50
	s_mov_b32 s20, s54
	s_cbranch_scc0 .LBB0_1827
	s_and_b64 vcc, exec, s[12:13]
	s_cbranch_vccz .LBB0_1830
	s_barrier
